# retkv epilogue lane-pair exchange via DPP quad_perm instead of ds_bpermute; quant_rows amax via DPP/permlane swaps
# baseline (speedup 1.0000x reference)
; __device__ __forceinline__ void quant_rows(const bf16_t* xb, unsigned char* xq, float* qs, const float* ssq, unsigned* cnt, int pm, int quarter, LAS float* rsl, int tid_) {
;     ...
; #pragma unroll
;         for (int q = 0; q < 4; ++q)
; #pragma unroll
;             for (int j = 0; j < 4; ++j) v[q][j] = *(const u32x4*)(xb + (size_t)(rbase + q) * DM + (j * 64 + lane) * 8);
; #pragma unroll
;         for (int q = 0; q < 4; ++q) {
;             unsigned mx = 0u;
; #pragma unroll
;             for (int j = 0; j < 4; ++j)
; #pragma unroll
;                 for (int e = 0; e < 4; ++e) { const unsigned w = v[q][j][e]; mx = max(mx, max(w & 0x7fffu, (w >> 16) & 0x7fffu)); }
; #pragma unroll
;             for (int o = 1; o < 64; o <<= 1) mx = max(mx, (unsigned)__shfl_xor((int)mx, o));
;             const float amax = __uint_as_float(mx << 16);
;             const float inv = mx ? 127.0f / amax : 0.f;
; #pragma unroll
;             for (int j = 0; j < 4; ++j) { float f[8]; unpack8(v[q][j], f); unsigned b[8];
; #pragma unroll
;                 for (int e = 0; e < 8; ++e) b[e] = __float_as_uint(__builtin_fmaf(f[e], inv, QMAGIC));
;                 u32x2 o; o.x = pack4q(b[0], b[1], b[2], b[3]); o.y = pack4q(b[4], b[5], b[6], b[7]);
;                 *(u32x2*)(xq + (size_t)(rbase + q) * DM + (j * 64 + lane) * 8) = o; }
;             if (lane == 0) qs[rbase + q] = amax * (1.0f / 127.0f);
.LBB0_131:
	s_or_b32 s22, s8, s26
	s_ashr_i32 s23, s22, 31
	s_lshl_b64 s[8:9], s[22:23], 12
	v_lshl_add_u64 v[2:3], v[66:67], 0, s[8:9]
	global_load_dwordx4 v[62:65], v[2:3], off
	global_load_dwordx4 v[58:61], v[2:3], off offset:1024
	global_load_dwordx4 v[54:57], v[2:3], off offset:2048
	global_load_dwordx4 v[46:49], v[2:3], off offset:3072
	s_or_b32 s20, s22, 1
	s_ashr_i32 s21, s20, 31
	s_lshl_b64 s[34:35], s[20:21], 12
	v_lshl_add_u64 v[2:3], v[66:67], 0, s[34:35]
	global_load_dwordx4 v[50:53], v[2:3], off
	global_load_dwordx4 v[42:45], v[2:3], off offset:1024
	global_load_dwordx4 v[38:41], v[2:3], off offset:2048
	global_load_dwordx4 v[34:37], v[2:3], off offset:3072
	s_or_b32 s18, s22, 2
	s_or_b32 s16, s22, 3
	s_ashr_i32 s19, s18, 31
	s_ashr_i32 s17, s16, 31
	s_lshl_b64 s[36:37], s[18:19], 12
	s_lshl_b64 s[38:39], s[16:17], 12
	v_lshl_add_u64 v[4:5], v[66:67], 0, s[36:37]
	v_lshl_add_u64 v[80:81], v[66:67], 0, s[38:39]
	s_lshl_b64 s[8:9], s[22:23], 11
	v_lshl_add_u64 v[70:71], v[68:69], 0, s[8:9]
	s_waitcnt vmcnt(0)
	v_and_b32_e32 v6, 0x7fff, v63
	v_bfe_u32 v7, v63, 16, 15
	v_and_b32_e32 v2, 0x7fff, v62
	v_bfe_u32 v3, v62, 16, 15
	v_and_b32_e32 v8, 0x7fff, v64
	v_bfe_u32 v9, v64, 16, 15
	v_and_b32_e32 v10, 0x7fff, v65
	v_bfe_u32 v11, v65, 16, 15
	v_max_u32_e32 v6, v6, v7
	s_waitcnt vmcnt(6)
	v_and_b32_e32 v12, 0x7fff, v58
	v_bfe_u32 v13, v58, 16, 15
	v_and_b32_e32 v14, 0x7fff, v59
	v_bfe_u32 v15, v59, 16, 15
	v_max_u32_e32 v7, v8, v9
	v_max_u32_e32 v8, v10, v11
	v_max3_u32 v2, v2, v3, v6
	v_and_b32_e32 v16, 0x7fff, v60
	v_bfe_u32 v17, v60, 16, 15
	v_and_b32_e32 v18, 0x7fff, v61
	v_bfe_u32 v19, v61, 16, 15
	v_max_u32_e32 v9, v12, v13
	v_max_u32_e32 v10, v14, v15
	v_max3_u32 v2, v2, v7, v8
	s_waitcnt vmcnt(5)
	v_and_b32_e32 v20, 0x7fff, v54
	v_bfe_u32 v21, v54, 16, 15
	v_and_b32_e32 v22, 0x7fff, v55
	v_bfe_u32 v23, v55, 16, 15
	v_max_u32_e32 v11, v16, v17
	v_max_u32_e32 v12, v18, v19
	v_max3_u32 v2, v2, v9, v10
	v_and_b32_e32 v24, 0x7fff, v56
	v_bfe_u32 v25, v56, 16, 15
	v_and_b32_e32 v26, 0x7fff, v57
	v_bfe_u32 v27, v57, 16, 15
	v_max_u32_e32 v13, v20, v21
	v_max_u32_e32 v14, v22, v23
	v_max3_u32 v2, v2, v11, v12
	s_waitcnt vmcnt(4)
	v_and_b32_e32 v28, 0x7fff, v46
	v_bfe_u32 v29, v46, 16, 15
	v_and_b32_e32 v30, 0x7fff, v47
	v_bfe_u32 v31, v47, 16, 15
	v_max_u32_e32 v15, v24, v25
	v_max_u32_e32 v16, v26, v27
	v_max3_u32 v2, v2, v13, v14
	v_and_b32_e32 v32, 0x7fff, v48
	v_bfe_u32 v33, v48, 16, 15
	v_and_b32_e32 v79, 0x7fff, v49
	v_bfe_u32 v82, v49, 16, 15
	v_max_u32_e32 v17, v28, v29
	v_max_u32_e32 v18, v30, v31
	v_max3_u32 v2, v2, v15, v16
	v_max_u32_e32 v19, v32, v33
	v_max_u32_e32 v20, v79, v82
	v_max3_u32 v2, v2, v17, v18
	v_max3_u32 v2, v2, v19, v20
	global_load_dwordx4 v[30:33], v[4:5], off
	global_load_dwordx4 v[26:29], v[4:5], off offset:1024
	global_load_dwordx4 v[22:25], v[4:5], off offset:2048
	global_load_dwordx4 v[18:21], v[4:5], off offset:3072
	v_lshlrev_b32_e32 v85, 16, v58
	v_and_b32_e32 v86, 0xffff0000, v58
	v_and_b32_e32 v88, 0xffff0000, v60
	s_waitcnt lgkmcnt(0)
	s_nop 1
	v_max_u32_dpp v79, v2, v2 quad_perm:[1,0,3,2] row_mask:0xf bank_mask:0xf
	global_load_dwordx4 v[14:17], v[80:81], off
	global_load_dwordx4 v[10:13], v[80:81], off offset:1024
	global_load_dwordx4 v[6:9], v[80:81], off offset:2048
	global_load_dwordx4 v[2:5], v[80:81], off offset:3072
	v_lshlrev_b32_e32 v89, 16, v61
	v_and_b32_e32 v90, 0xffff0000, v61
	v_lshlrev_b32_e32 v81, 16, v62
	v_and_b32_e32 v62, 0xffff0000, v62
	s_waitcnt lgkmcnt(0)
	s_nop 1
	v_max_u32_dpp v79, v79, v79 quad_perm:[2,3,0,1] row_mask:0xf bank_mask:0xf
	v_lshlrev_b32_e32 v82, 16, v63
	v_and_b32_e32 v63, 0xffff0000, v63
	v_lshlrev_b32_e32 v83, 16, v64
	v_and_b32_e32 v64, 0xffff0000, v64
	s_waitcnt lgkmcnt(0)
	s_nop 1
	v_max_u32_dpp v79, v79, v79 row_half_mirror row_mask:0xf bank_mask:0xf
	v_lshlrev_b32_e32 v84, 16, v65
	v_and_b32_e32 v65, 0xffff0000, v65
	v_lshlrev_b32_e32 v87, 16, v59
	v_and_b32_e32 v59, 0xffff0000, v59
	s_waitcnt lgkmcnt(0)
	s_nop 1
	v_max_u32_dpp v79, v79, v79 row_mirror row_mask:0xf bank_mask:0xf
	s_waitcnt lgkmcnt(0)
	v_mov_b32_e32 v80, v79
	s_nop 1
	v_permlane16_swap_b32_e32 v79, v80
	v_max_u32_e32 v58, v79, v80
	v_lshlrev_b32_e32 v80, 16, v60
	s_waitcnt lgkmcnt(0)
	v_mov_b32_e32 v79, v58
	s_nop 1
	v_permlane32_swap_b32_e32 v58, v79
	v_max_u32_e32 v60, v58, v79
	v_lshlrev_b32_e32 v58, 16, v60
	v_div_scale_f32 v61, s[8:9], v58, v58, s87
	v_rcp_f32_e32 v79, v61
	v_cmp_ne_u32_e64 s[8:9], 0, v60
	v_div_scale_f32 v60, vcc, s87, v58, s87
	v_fma_f32 v91, -v61, v79, 1.0
	v_fmac_f32_e32 v79, v91, v79
	v_mul_f32_e32 v91, v60, v79
	v_fma_f32 v92, -v61, v91, v60
	v_fmac_f32_e32 v91, v92, v79
	v_fma_f32 v60, -v61, v91, v60
	v_div_fmas_f32 v60, v60, v79, v91
	v_div_fixup_f32 v60, v60, v58, s87
	v_cndmask_b32_e64 v79, 0, v60, s[8:9]
	v_fmaak_f32 v60, v81, v79, 0x4b400000
	v_fmaak_f32 v61, v62, v79, 0x4b400000
	v_fmaak_f32 v62, v82, v79, 0x4b400000
	v_fmaak_f32 v63, v63, v79, 0x4b400000
	v_fmaak_f32 v81, v83, v79, 0x4b400000
	v_fmaak_f32 v64, v64, v79, 0x4b400000
	v_fmaak_f32 v82, v84, v79, 0x4b400000
	v_fmaak_f32 v65, v65, v79, 0x4b400000
	v_perm_b32 v60, v61, v60, s3
	v_perm_b32 v61, v63, v62, s33
	v_perm_b32 v62, v64, v81, s3
	v_perm_b32 v63, v65, v82, s33
	v_or_b32_e32 v60, v61, v60
	v_or_b32_e32 v61, v63, v62
	global_store_dwordx2 v[70:71], v[60:61], off
	v_fmaak_f32 v60, v85, v79, 0x4b400000
	v_fmaak_f32 v61, v86, v79, 0x4b400000
	v_fmaak_f32 v62, v87, v79, 0x4b400000
	v_fmaak_f32 v59, v59, v79, 0x4b400000
	v_fmaak_f32 v63, v80, v79, 0x4b400000
	v_fmaak_f32 v64, v88, v79, 0x4b400000
	v_fmaak_f32 v65, v89, v79, 0x4b400000
	v_fmaak_f32 v80, v90, v79, 0x4b400000
; __device__ __forceinline__ void quant_rows(const bf16_t* xb, unsigned char* xq, float* qs, const float* ssq, unsigned* cnt, int pm, int quarter, LAS float* rsl, int tid_) {
;     ...
;         for (int q = 0; q < 4; ++q) {
;             unsigned mx = 0u;
; #pragma unroll
;             for (int j = 0; j < 4; ++j)
; #pragma unroll
;                 for (int e = 0; e < 4; ++e) { const unsigned w = v[q][j][e]; mx = max(mx, max(w & 0x7fffu, (w >> 16) & 0x7fffu)); }
; #pragma unroll
;             for (int o = 1; o < 64; o <<= 1) mx = max(mx, (unsigned)__shfl_xor((int)mx, o));
;             const float amax = __uint_as_float(mx << 16);
;             const float inv = mx ? 127.0f / amax : 0.f;
; #pragma unroll
;             for (int j = 0; j < 4; ++j) { float f[8]; unpack8(v[q][j], f); unsigned b[8];
; #pragma unroll
;                 for (int e = 0; e < 8; ++e) b[e] = __float_as_uint(__builtin_fmaf(f[e], inv, QMAGIC));
;                 u32x2 o; o.x = pack4q(b[0], b[1], b[2], b[3]); o.y = pack4q(b[4], b[5], b[6], b[7]);
;                 *(u32x2*)(xq + (size_t)(rbase + q) * DM + (j * 64 + lane) * 8) = o; }
;             if (lane == 0) qs[rbase + q] = amax * (1.0f / 127.0f);
	v_perm_b32 v60, v61, v60, s3
	v_perm_b32 v59, v59, v62, s33
	v_or_b32_e32 v60, v59, v60
	v_perm_b32 v59, v64, v63, s3
	v_perm_b32 v61, v80, v65, s33
	v_or_b32_e32 v61, v61, v59
	global_store_dwordx2 v[70:71], v[60:61], off offset:512
	v_lshlrev_b32_e32 v59, 16, v54
	v_and_b32_e32 v54, 0xffff0000, v54
	v_lshlrev_b32_e32 v60, 16, v55
	v_and_b32_e32 v55, 0xffff0000, v55
	v_lshlrev_b32_e32 v61, 16, v56
	v_and_b32_e32 v56, 0xffff0000, v56
	v_lshlrev_b32_e32 v62, 16, v57
	v_and_b32_e32 v57, 0xffff0000, v57
	v_fmaak_f32 v59, v59, v79, 0x4b400000
	v_fmaak_f32 v54, v54, v79, 0x4b400000
	v_fmaak_f32 v60, v60, v79, 0x4b400000
	v_fmaak_f32 v55, v55, v79, 0x4b400000
	v_fmaak_f32 v61, v61, v79, 0x4b400000
	v_fmaak_f32 v56, v56, v79, 0x4b400000
	v_fmaak_f32 v62, v62, v79, 0x4b400000
	v_fmaak_f32 v57, v57, v79, 0x4b400000
	v_perm_b32 v54, v54, v59, s3
	v_perm_b32 v55, v55, v60, s33
	v_or_b32_e32 v54, v55, v54
	v_perm_b32 v55, v56, v61, s3
	v_perm_b32 v56, v57, v62, s33
	v_or_b32_e32 v55, v56, v55
	global_store_dwordx2 v[70:71], v[54:55], off offset:1024
	v_lshlrev_b32_e32 v54, 16, v46
	v_and_b32_e32 v46, 0xffff0000, v46
	v_lshlrev_b32_e32 v55, 16, v47
	v_and_b32_e32 v47, 0xffff0000, v47
	v_lshlrev_b32_e32 v56, 16, v48
	v_and_b32_e32 v48, 0xffff0000, v48
	v_lshlrev_b32_e32 v57, 16, v49
	v_and_b32_e32 v49, 0xffff0000, v49
	v_fmaak_f32 v54, v54, v79, 0x4b400000
	v_fmaak_f32 v46, v46, v79, 0x4b400000
	v_fmaak_f32 v55, v55, v79, 0x4b400000
	v_fmaak_f32 v47, v47, v79, 0x4b400000
	v_fmaak_f32 v56, v56, v79, 0x4b400000
	v_fmaak_f32 v48, v48, v79, 0x4b400000
	v_fmaak_f32 v57, v57, v79, 0x4b400000
	v_fmaak_f32 v49, v49, v79, 0x4b400000
	v_perm_b32 v46, v46, v54, s3
	v_perm_b32 v47, v47, v55, s33
	v_or_b32_e32 v46, v47, v46
	v_perm_b32 v47, v48, v56, s3
	v_perm_b32 v48, v49, v57, s33
	v_or_b32_e32 v47, v48, v47
	global_store_dwordx2 v[70:71], v[46:47], off offset:1536
	s_and_saveexec_b64 s[8:9], s[6:7]
	s_cbranch_execz .LBB0_133
	s_lshl_b64 s[22:23], s[22:23], 2
	s_add_u32 s22, s12, s22
	v_mul_f32_e32 v46, 0x3c010204, v58
	s_addc_u32 s23, s13, s23
	global_store_dword v163, v46, s[22:23]
.LBB0_133:
	s_or_b64 exec, exec, s[8:9]
	s_waitcnt vmcnt(15)
	v_and_b32_e32 v48, 0x7fff, v51
	v_bfe_u32 v49, v51, 16, 15
	v_and_b32_e32 v46, 0x7fff, v50
	v_bfe_u32 v47, v50, 16, 15
	v_max_u32_e32 v48, v48, v49
	v_max3_u32 v46, v46, v47, v48
	v_and_b32_e32 v47, 0x7fff, v52
	v_bfe_u32 v48, v52, 16, 15
	v_max_u32_e32 v47, v47, v48
	v_and_b32_e32 v48, 0x7fff, v53
	v_bfe_u32 v49, v53, 16, 15
	v_max_u32_e32 v48, v48, v49
	v_max3_u32 v46, v46, v47, v48
	s_waitcnt vmcnt(14)
	v_and_b32_e32 v47, 0x7fff, v42
	v_bfe_u32 v48, v42, 16, 15
	v_max_u32_e32 v47, v47, v48
	v_and_b32_e32 v48, 0x7fff, v43
	v_bfe_u32 v49, v43, 16, 15
	v_max_u32_e32 v48, v48, v49
	v_max3_u32 v46, v46, v47, v48
	v_and_b32_e32 v47, 0x7fff, v44
	v_bfe_u32 v48, v44, 16, 15
	v_max_u32_e32 v47, v47, v48
	v_and_b32_e32 v48, 0x7fff, v45
	v_bfe_u32 v49, v45, 16, 15
	v_max_u32_e32 v48, v48, v49
	v_max3_u32 v46, v46, v47, v48
	s_waitcnt vmcnt(13)
	v_and_b32_e32 v47, 0x7fff, v38
	v_bfe_u32 v48, v38, 16, 15
	v_max_u32_e32 v47, v47, v48
	v_and_b32_e32 v48, 0x7fff, v39
	v_bfe_u32 v49, v39, 16, 15
	v_max_u32_e32 v48, v48, v49
	v_max3_u32 v46, v46, v47, v48
	v_and_b32_e32 v47, 0x7fff, v40
	v_bfe_u32 v48, v40, 16, 15
	v_max_u32_e32 v47, v47, v48
	v_and_b32_e32 v48, 0x7fff, v41
	v_bfe_u32 v49, v41, 16, 15
	v_max_u32_e32 v48, v48, v49
	v_max3_u32 v46, v46, v47, v48
	s_waitcnt vmcnt(12)
	v_and_b32_e32 v47, 0x7fff, v34
	v_bfe_u32 v48, v34, 16, 15
	v_max_u32_e32 v47, v47, v48
	v_and_b32_e32 v48, 0x7fff, v35
	v_bfe_u32 v49, v35, 16, 15
	v_max_u32_e32 v48, v48, v49
	v_max3_u32 v46, v46, v47, v48
	v_and_b32_e32 v47, 0x7fff, v36
	v_bfe_u32 v48, v36, 16, 15
	v_max_u32_e32 v47, v47, v48
	v_and_b32_e32 v48, 0x7fff, v37
	v_bfe_u32 v49, v37, 16, 15
	v_max_u32_e32 v48, v48, v49
	v_max3_u32 v46, v46, v47, v48
	s_waitcnt lgkmcnt(0)
	s_nop 1
	v_max_u32_dpp v46, v46, v46 quad_perm:[1,0,3,2] row_mask:0xf bank_mask:0xf
	s_waitcnt lgkmcnt(0)
	s_nop 1
	v_max_u32_dpp v46, v46, v46 quad_perm:[2,3,0,1] row_mask:0xf bank_mask:0xf
	s_waitcnt lgkmcnt(0)
	s_nop 1
	v_max_u32_dpp v46, v46, v46 row_half_mirror row_mask:0xf bank_mask:0xf
	s_waitcnt lgkmcnt(0)
	s_nop 1
	v_max_u32_dpp v46, v46, v46 row_mirror row_mask:0xf bank_mask:0xf
	s_waitcnt lgkmcnt(0)
	v_mov_b32_e32 v47, v46
	s_nop 1
	v_permlane16_swap_b32_e32 v46, v47
	v_max_u32_e32 v46, v46, v47
	s_waitcnt lgkmcnt(0)
; __device__ __forceinline__ void quant_rows(const bf16_t* xb, unsigned char* xq, float* qs, const float* ssq, unsigned* cnt, int pm, int quarter, LAS float* rsl, int tid_) {
;     ...
;         for (int q = 0; q < 4; ++q) {
;             unsigned mx = 0u;
; #pragma unroll
;             for (int j = 0; j < 4; ++j)
; #pragma unroll
;                 for (int e = 0; e < 4; ++e) { const unsigned w = v[q][j][e]; mx = max(mx, max(w & 0x7fffu, (w >> 16) & 0x7fffu)); }
; #pragma unroll
;             for (int o = 1; o < 64; o <<= 1) mx = max(mx, (unsigned)__shfl_xor((int)mx, o));
;             const float amax = __uint_as_float(mx << 16);
;             const float inv = mx ? 127.0f / amax : 0.f;
; #pragma unroll
;             for (int j = 0; j < 4; ++j) { float f[8]; unpack8(v[q][j], f); unsigned b[8];
; #pragma unroll
;                 for (int e = 0; e < 8; ++e) b[e] = __float_as_uint(__builtin_fmaf(f[e], inv, QMAGIC));
;                 u32x2 o; o.x = pack4q(b[0], b[1], b[2], b[3]); o.y = pack4q(b[4], b[5], b[6], b[7]);
;                 *(u32x2*)(xq + (size_t)(rbase + q) * DM + (j * 64 + lane) * 8) = o; }
;             if (lane == 0) qs[rbase + q] = amax * (1.0f / 127.0f);
	v_mov_b32_e32 v47, v46
	s_nop 1
	v_permlane32_swap_b32_e32 v46, v47
	v_max_u32_e32 v47, v46, v47
	v_lshlrev_b32_e32 v46, 16, v47
	v_div_scale_f32 v48, s[8:9], v46, v46, s87
	v_rcp_f32_e32 v49, v48
	s_lshl_b64 s[8:9], s[20:21], 11
	v_fma_f32 v54, -v48, v49, 1.0
	v_fmac_f32_e32 v49, v54, v49
	v_div_scale_f32 v54, vcc, s87, v46, s87
	v_mul_f32_e32 v55, v54, v49
	v_fma_f32 v56, -v48, v55, v54
	v_fmac_f32_e32 v55, v56, v49
	v_fma_f32 v48, -v48, v55, v54
	v_div_fmas_f32 v48, v48, v49, v55
	v_div_fixup_f32 v48, v48, v46, s87
	v_cmp_ne_u32_e32 vcc, 0, v47
	v_and_b32_e32 v49, 0xffff0000, v50
	v_lshlrev_b32_e32 v54, 16, v52
	v_cndmask_b32_e32 v47, 0, v48, vcc
	v_lshlrev_b32_e32 v48, 16, v50
	v_lshlrev_b32_e32 v50, 16, v51
	v_and_b32_e32 v51, 0xffff0000, v51
	v_and_b32_e32 v52, 0xffff0000, v52
	v_lshlrev_b32_e32 v55, 16, v53
	v_and_b32_e32 v53, 0xffff0000, v53
	v_fmaak_f32 v48, v48, v47, 0x4b400000
	v_fmaak_f32 v49, v49, v47, 0x4b400000
	v_fmaak_f32 v50, v50, v47, 0x4b400000
	v_fmaak_f32 v51, v51, v47, 0x4b400000
	v_fmaak_f32 v54, v54, v47, 0x4b400000
	v_fmaak_f32 v52, v52, v47, 0x4b400000
	v_fmaak_f32 v55, v55, v47, 0x4b400000
	v_fmaak_f32 v53, v53, v47, 0x4b400000
	v_perm_b32 v48, v49, v48, s3
	v_perm_b32 v49, v51, v50, s33
	v_or_b32_e32 v48, v49, v48
	v_perm_b32 v49, v52, v54, s3
	v_perm_b32 v50, v53, v55, s33
	v_or_b32_e32 v49, v50, v49
	v_lshl_add_u64 v[50:51], v[68:69], 0, s[8:9]
	global_store_dwordx2 v[50:51], v[48:49], off
	v_lshlrev_b32_e32 v48, 16, v42
	v_and_b32_e32 v42, 0xffff0000, v42
	v_lshlrev_b32_e32 v49, 16, v43
	v_and_b32_e32 v43, 0xffff0000, v43
	v_lshlrev_b32_e32 v52, 16, v44
	v_and_b32_e32 v44, 0xffff0000, v44
	v_lshlrev_b32_e32 v53, 16, v45
	v_and_b32_e32 v45, 0xffff0000, v45
	v_fmaak_f32 v48, v48, v47, 0x4b400000
	v_fmaak_f32 v42, v42, v47, 0x4b400000
	v_fmaak_f32 v49, v49, v47, 0x4b400000
	v_fmaak_f32 v43, v43, v47, 0x4b400000
	v_fmaak_f32 v52, v52, v47, 0x4b400000
	v_fmaak_f32 v44, v44, v47, 0x4b400000
	v_fmaak_f32 v53, v53, v47, 0x4b400000
	v_fmaak_f32 v45, v45, v47, 0x4b400000
	v_perm_b32 v42, v42, v48, s3
	v_perm_b32 v43, v43, v49, s33
	v_or_b32_e32 v42, v43, v42
	v_perm_b32 v43, v44, v52, s3
	v_perm_b32 v44, v45, v53, s33
	v_or_b32_e32 v43, v44, v43
	global_store_dwordx2 v[50:51], v[42:43], off offset:512
	v_lshlrev_b32_e32 v42, 16, v38
	v_and_b32_e32 v38, 0xffff0000, v38
	v_lshlrev_b32_e32 v43, 16, v39
	v_and_b32_e32 v39, 0xffff0000, v39
	v_lshlrev_b32_e32 v44, 16, v40
	v_and_b32_e32 v40, 0xffff0000, v40
	v_lshlrev_b32_e32 v45, 16, v41
	v_and_b32_e32 v41, 0xffff0000, v41
	v_fmaak_f32 v42, v42, v47, 0x4b400000
	v_fmaak_f32 v38, v38, v47, 0x4b400000
	v_fmaak_f32 v43, v43, v47, 0x4b400000
	v_fmaak_f32 v39, v39, v47, 0x4b400000
	v_fmaak_f32 v44, v44, v47, 0x4b400000
	v_fmaak_f32 v40, v40, v47, 0x4b400000
	v_fmaak_f32 v45, v45, v47, 0x4b400000
	v_fmaak_f32 v41, v41, v47, 0x4b400000
	v_perm_b32 v38, v38, v42, s3
	v_perm_b32 v39, v39, v43, s33
	v_or_b32_e32 v38, v39, v38
	v_perm_b32 v39, v40, v44, s3
	v_perm_b32 v40, v41, v45, s33
	v_or_b32_e32 v39, v40, v39
	global_store_dwordx2 v[50:51], v[38:39], off offset:1024
	v_lshlrev_b32_e32 v38, 16, v34
	v_and_b32_e32 v34, 0xffff0000, v34
	v_lshlrev_b32_e32 v39, 16, v35
	v_and_b32_e32 v35, 0xffff0000, v35
	v_lshlrev_b32_e32 v40, 16, v36
	v_and_b32_e32 v36, 0xffff0000, v36
	v_lshlrev_b32_e32 v41, 16, v37
	v_and_b32_e32 v37, 0xffff0000, v37
	v_fmaak_f32 v38, v38, v47, 0x4b400000
	v_fmaak_f32 v34, v34, v47, 0x4b400000
	v_fmaak_f32 v39, v39, v47, 0x4b400000
	v_fmaak_f32 v35, v35, v47, 0x4b400000
	v_fmaak_f32 v40, v40, v47, 0x4b400000
	v_fmaak_f32 v36, v36, v47, 0x4b400000
	v_fmaak_f32 v41, v41, v47, 0x4b400000
	v_fmaak_f32 v37, v37, v47, 0x4b400000
	v_perm_b32 v34, v34, v38, s3
	v_perm_b32 v35, v35, v39, s33
	v_or_b32_e32 v34, v35, v34
	v_perm_b32 v35, v36, v40, s3
	v_perm_b32 v36, v37, v41, s33
	v_or_b32_e32 v35, v36, v35
	global_store_dwordx2 v[50:51], v[34:35], off offset:1536
	s_and_saveexec_b64 s[8:9], s[6:7]
	s_cbranch_execz .LBB0_135
	s_lshl_b64 s[20:21], s[20:21], 2
	s_add_u32 s20, s12, s20
	v_mul_f32_e32 v34, 0x3c010204, v46
	s_addc_u32 s21, s13, s21
	global_store_dword v163, v34, s[20:21]
.LBB0_135:
	s_or_b64 exec, exec, s[8:9]
	s_waitcnt vmcnt(15)
	v_and_b32_e32 v36, 0x7fff, v31
	v_bfe_u32 v37, v31, 16, 15
	v_and_b32_e32 v34, 0x7fff, v30
	v_bfe_u32 v35, v30, 16, 15
	v_max_u32_e32 v36, v36, v37
	v_max3_u32 v34, v34, v35, v36
	v_and_b32_e32 v35, 0x7fff, v32
	v_bfe_u32 v36, v32, 16, 15
	v_max_u32_e32 v35, v35, v36
	v_and_b32_e32 v36, 0x7fff, v33
	v_bfe_u32 v37, v33, 16, 15
	v_max_u32_e32 v36, v36, v37
	v_max3_u32 v34, v34, v35, v36
	s_waitcnt vmcnt(14)
	v_and_b32_e32 v35, 0x7fff, v26
	v_bfe_u32 v36, v26, 16, 15
	v_max_u32_e32 v35, v35, v36
	v_and_b32_e32 v36, 0x7fff, v27
	v_bfe_u32 v37, v27, 16, 15
	v_max_u32_e32 v36, v36, v37
	v_max3_u32 v34, v34, v35, v36
	v_and_b32_e32 v35, 0x7fff, v28
	v_bfe_u32 v36, v28, 16, 15
	v_max_u32_e32 v35, v35, v36
	v_and_b32_e32 v36, 0x7fff, v29
	v_bfe_u32 v37, v29, 16, 15
	v_max_u32_e32 v36, v36, v37
	v_max3_u32 v34, v34, v35, v36
	s_waitcnt vmcnt(13)
	v_and_b32_e32 v35, 0x7fff, v22
	v_bfe_u32 v36, v22, 16, 15
	v_max_u32_e32 v35, v35, v36
	v_and_b32_e32 v36, 0x7fff, v23
	v_bfe_u32 v37, v23, 16, 15
	v_max_u32_e32 v36, v36, v37
	v_max3_u32 v34, v34, v35, v36
	v_and_b32_e32 v35, 0x7fff, v24
	v_bfe_u32 v36, v24, 16, 15
	v_max_u32_e32 v35, v35, v36
	v_and_b32_e32 v36, 0x7fff, v25
	v_bfe_u32 v37, v25, 16, 15
	v_max_u32_e32 v36, v36, v37
	v_max3_u32 v34, v34, v35, v36
	s_waitcnt vmcnt(12)
; __device__ __forceinline__ void quant_rows(const bf16_t* xb, unsigned char* xq, float* qs, const float* ssq, unsigned* cnt, int pm, int quarter, LAS float* rsl, int tid_) {
;     ...
;         for (int q = 0; q < 4; ++q) {
;             unsigned mx = 0u;
; #pragma unroll
;             for (int j = 0; j < 4; ++j)
; #pragma unroll
;                 for (int e = 0; e < 4; ++e) { const unsigned w = v[q][j][e]; mx = max(mx, max(w & 0x7fffu, (w >> 16) & 0x7fffu)); }
; #pragma unroll
;             for (int o = 1; o < 64; o <<= 1) mx = max(mx, (unsigned)__shfl_xor((int)mx, o));
;             const float amax = __uint_as_float(mx << 16);
;             const float inv = mx ? 127.0f / amax : 0.f;
; #pragma unroll
;             for (int j = 0; j < 4; ++j) { float f[8]; unpack8(v[q][j], f); unsigned b[8];
; #pragma unroll
;                 for (int e = 0; e < 8; ++e) b[e] = __float_as_uint(__builtin_fmaf(f[e], inv, QMAGIC));
;                 u32x2 o; o.x = pack4q(b[0], b[1], b[2], b[3]); o.y = pack4q(b[4], b[5], b[6], b[7]);
;                 *(u32x2*)(xq + (size_t)(rbase + q) * DM + (j * 64 + lane) * 8) = o; }
;             if (lane == 0) qs[rbase + q] = amax * (1.0f / 127.0f);
	v_and_b32_e32 v35, 0x7fff, v18
	v_bfe_u32 v36, v18, 16, 15
	v_max_u32_e32 v35, v35, v36
	v_and_b32_e32 v36, 0x7fff, v19
	v_bfe_u32 v37, v19, 16, 15
	v_max_u32_e32 v36, v36, v37
	v_max3_u32 v34, v34, v35, v36
	v_and_b32_e32 v35, 0x7fff, v20
	v_bfe_u32 v36, v20, 16, 15
	v_max_u32_e32 v35, v35, v36
	v_and_b32_e32 v36, 0x7fff, v21
	v_bfe_u32 v37, v21, 16, 15
	v_max_u32_e32 v36, v36, v37
	v_max3_u32 v34, v34, v35, v36
	s_waitcnt lgkmcnt(0)
	s_nop 1
	v_max_u32_dpp v34, v34, v34 quad_perm:[1,0,3,2] row_mask:0xf bank_mask:0xf
	s_waitcnt lgkmcnt(0)
	s_nop 1
	v_max_u32_dpp v34, v34, v34 quad_perm:[2,3,0,1] row_mask:0xf bank_mask:0xf
	s_waitcnt lgkmcnt(0)
	s_nop 1
	v_max_u32_dpp v34, v34, v34 row_half_mirror row_mask:0xf bank_mask:0xf
	s_waitcnt lgkmcnt(0)
	s_nop 1
	v_max_u32_dpp v34, v34, v34 row_mirror row_mask:0xf bank_mask:0xf
	s_waitcnt lgkmcnt(0)
	v_mov_b32_e32 v35, v34
	s_nop 1
	v_permlane16_swap_b32_e32 v34, v35
	v_max_u32_e32 v34, v34, v35
	s_waitcnt lgkmcnt(0)
	v_mov_b32_e32 v35, v34
	s_nop 1
	v_permlane32_swap_b32_e32 v34, v35
	v_max_u32_e32 v35, v34, v35
	v_lshlrev_b32_e32 v34, 16, v35
	v_div_scale_f32 v36, s[8:9], v34, v34, s87
	v_rcp_f32_e32 v37, v36
	s_lshl_b64 s[8:9], s[18:19], 11
	v_fma_f32 v38, -v36, v37, 1.0
	v_fmac_f32_e32 v37, v38, v37
	v_div_scale_f32 v38, vcc, s87, v34, s87
	v_mul_f32_e32 v39, v38, v37
	v_fma_f32 v40, -v36, v39, v38
	v_fmac_f32_e32 v39, v40, v37
	v_fma_f32 v36, -v36, v39, v38
	v_div_fmas_f32 v36, v36, v37, v39
	v_div_fixup_f32 v36, v36, v34, s87
	v_cmp_ne_u32_e32 vcc, 0, v35
	v_lshlrev_b32_e32 v37, 16, v31
	v_and_b32_e32 v31, 0xffff0000, v31
	v_cndmask_b32_e32 v35, 0, v36, vcc
	v_lshlrev_b32_e32 v36, 16, v30
	v_and_b32_e32 v30, 0xffff0000, v30
	v_lshlrev_b32_e32 v38, 16, v32
	v_and_b32_e32 v32, 0xffff0000, v32
	v_lshlrev_b32_e32 v39, 16, v33
	v_and_b32_e32 v33, 0xffff0000, v33
	v_fmaak_f32 v36, v36, v35, 0x4b400000
	v_fmaak_f32 v30, v30, v35, 0x4b400000
	v_fmaak_f32 v37, v37, v35, 0x4b400000
	v_fmaak_f32 v31, v31, v35, 0x4b400000
	v_fmaak_f32 v38, v38, v35, 0x4b400000
	v_fmaak_f32 v32, v32, v35, 0x4b400000
	v_fmaak_f32 v39, v39, v35, 0x4b400000
	v_fmaak_f32 v33, v33, v35, 0x4b400000
	v_perm_b32 v30, v30, v36, s3
	v_perm_b32 v31, v31, v37, s33
	v_or_b32_e32 v30, v31, v30
	v_perm_b32 v31, v32, v38, s3
	v_perm_b32 v32, v33, v39, s33
	v_or_b32_e32 v31, v32, v31
	v_lshl_add_u64 v[32:33], v[68:69], 0, s[8:9]
	global_store_dwordx2 v[32:33], v[30:31], off
	v_lshlrev_b32_e32 v30, 16, v26
	v_and_b32_e32 v26, 0xffff0000, v26
	v_lshlrev_b32_e32 v31, 16, v27
	v_and_b32_e32 v27, 0xffff0000, v27
	v_lshlrev_b32_e32 v36, 16, v28
	v_and_b32_e32 v28, 0xffff0000, v28
	v_lshlrev_b32_e32 v37, 16, v29
	v_and_b32_e32 v29, 0xffff0000, v29
	v_fmaak_f32 v30, v30, v35, 0x4b400000
	v_fmaak_f32 v26, v26, v35, 0x4b400000
	v_fmaak_f32 v31, v31, v35, 0x4b400000
	v_fmaak_f32 v27, v27, v35, 0x4b400000
	v_fmaak_f32 v36, v36, v35, 0x4b400000
	v_fmaak_f32 v28, v28, v35, 0x4b400000
	v_fmaak_f32 v37, v37, v35, 0x4b400000
	v_fmaak_f32 v29, v29, v35, 0x4b400000
	v_perm_b32 v26, v26, v30, s3
	v_perm_b32 v27, v27, v31, s33
	v_or_b32_e32 v26, v27, v26
	v_perm_b32 v27, v28, v36, s3
	v_perm_b32 v28, v29, v37, s33
	v_or_b32_e32 v27, v28, v27
	global_store_dwordx2 v[32:33], v[26:27], off offset:512
	v_lshlrev_b32_e32 v26, 16, v22
	v_and_b32_e32 v22, 0xffff0000, v22
	v_lshlrev_b32_e32 v27, 16, v23
	v_and_b32_e32 v23, 0xffff0000, v23
	v_lshlrev_b32_e32 v28, 16, v24
	v_and_b32_e32 v24, 0xffff0000, v24
	v_lshlrev_b32_e32 v29, 16, v25
	v_and_b32_e32 v25, 0xffff0000, v25
	v_fmaak_f32 v26, v26, v35, 0x4b400000
	v_fmaak_f32 v22, v22, v35, 0x4b400000
	v_fmaak_f32 v27, v27, v35, 0x4b400000
	v_fmaak_f32 v23, v23, v35, 0x4b400000
	v_fmaak_f32 v28, v28, v35, 0x4b400000
	v_fmaak_f32 v24, v24, v35, 0x4b400000
	v_fmaak_f32 v29, v29, v35, 0x4b400000
	v_fmaak_f32 v25, v25, v35, 0x4b400000
	v_perm_b32 v22, v22, v26, s3
	v_perm_b32 v23, v23, v27, s33
	v_or_b32_e32 v22, v23, v22
	v_perm_b32 v23, v24, v28, s3
	v_perm_b32 v24, v25, v29, s33
	v_or_b32_e32 v23, v24, v23
	global_store_dwordx2 v[32:33], v[22:23], off offset:1024
	v_lshlrev_b32_e32 v22, 16, v18
	v_and_b32_e32 v18, 0xffff0000, v18
	v_lshlrev_b32_e32 v23, 16, v19
	v_and_b32_e32 v19, 0xffff0000, v19
	v_lshlrev_b32_e32 v24, 16, v20
	v_and_b32_e32 v20, 0xffff0000, v20
	v_lshlrev_b32_e32 v25, 16, v21
	v_and_b32_e32 v21, 0xffff0000, v21
	v_fmaak_f32 v22, v22, v35, 0x4b400000
	v_fmaak_f32 v18, v18, v35, 0x4b400000
	v_fmaak_f32 v23, v23, v35, 0x4b400000
	v_fmaak_f32 v19, v19, v35, 0x4b400000
	v_fmaak_f32 v24, v24, v35, 0x4b400000
	v_fmaak_f32 v20, v20, v35, 0x4b400000
	v_fmaak_f32 v25, v25, v35, 0x4b400000
	v_fmaak_f32 v21, v21, v35, 0x4b400000
	v_perm_b32 v18, v18, v22, s3
	v_perm_b32 v19, v19, v23, s33
	v_or_b32_e32 v18, v19, v18
	v_perm_b32 v19, v20, v24, s3
	v_perm_b32 v20, v21, v25, s33
	v_or_b32_e32 v19, v20, v19
	global_store_dwordx2 v[32:33], v[18:19], off offset:1536
	s_and_saveexec_b64 s[8:9], s[6:7]
	s_cbranch_execz .LBB0_137
	s_lshl_b64 s[18:19], s[18:19], 2
	s_add_u32 s18, s12, s18
	v_mul_f32_e32 v18, 0x3c010204, v34
	s_addc_u32 s19, s13, s19
	global_store_dword v163, v18, s[18:19]
; __device__ __forceinline__ void quant_rows(const bf16_t* xb, unsigned char* xq, float* qs, const float* ssq, unsigned* cnt, int pm, int quarter, LAS float* rsl, int tid_) {
;     ...
;         for (int q = 0; q < 4; ++q) {
;             unsigned mx = 0u;
; #pragma unroll
;             for (int j = 0; j < 4; ++j)
; #pragma unroll
;                 for (int e = 0; e < 4; ++e) { const unsigned w = v[q][j][e]; mx = max(mx, max(w & 0x7fffu, (w >> 16) & 0x7fffu)); }
; #pragma unroll
;             for (int o = 1; o < 64; o <<= 1) mx = max(mx, (unsigned)__shfl_xor((int)mx, o));
;             const float amax = __uint_as_float(mx << 16);
;             const float inv = mx ? 127.0f / amax : 0.f;
; #pragma unroll
;             for (int j = 0; j < 4; ++j) { float f[8]; unpack8(v[q][j], f); unsigned b[8];
; #pragma unroll
;                 for (int e = 0; e < 8; ++e) b[e] = __float_as_uint(__builtin_fmaf(f[e], inv, QMAGIC));
;                 u32x2 o; o.x = pack4q(b[0], b[1], b[2], b[3]); o.y = pack4q(b[4], b[5], b[6], b[7]);
;                 *(u32x2*)(xq + (size_t)(rbase + q) * DM + (j * 64 + lane) * 8) = o; }
;             if (lane == 0) qs[rbase + q] = amax * (1.0f / 127.0f);
.LBB0_137:
	s_or_b64 exec, exec, s[8:9]
	s_waitcnt vmcnt(15)
	v_and_b32_e32 v20, 0x7fff, v15
	v_bfe_u32 v21, v15, 16, 15
	v_and_b32_e32 v18, 0x7fff, v14
	v_bfe_u32 v19, v14, 16, 15
	v_max_u32_e32 v20, v20, v21
	v_max3_u32 v18, v18, v19, v20
	v_and_b32_e32 v19, 0x7fff, v16
	v_bfe_u32 v20, v16, 16, 15
	v_max_u32_e32 v19, v19, v20
	v_and_b32_e32 v20, 0x7fff, v17
	v_bfe_u32 v21, v17, 16, 15
	v_max_u32_e32 v20, v20, v21
	v_max3_u32 v18, v18, v19, v20
	s_waitcnt vmcnt(14)
	v_and_b32_e32 v19, 0x7fff, v10
	v_bfe_u32 v20, v10, 16, 15
	v_max_u32_e32 v19, v19, v20
	v_and_b32_e32 v20, 0x7fff, v11
	v_bfe_u32 v21, v11, 16, 15
	v_max_u32_e32 v20, v20, v21
	v_max3_u32 v18, v18, v19, v20
	v_and_b32_e32 v19, 0x7fff, v12
	v_bfe_u32 v20, v12, 16, 15
	v_max_u32_e32 v19, v19, v20
	v_and_b32_e32 v20, 0x7fff, v13
	v_bfe_u32 v21, v13, 16, 15
	v_max_u32_e32 v20, v20, v21
	v_max3_u32 v18, v18, v19, v20
	s_waitcnt vmcnt(13)
	v_and_b32_e32 v19, 0x7fff, v6
	v_bfe_u32 v20, v6, 16, 15
	v_max_u32_e32 v19, v19, v20
	v_and_b32_e32 v20, 0x7fff, v7
	v_bfe_u32 v21, v7, 16, 15
	v_max_u32_e32 v20, v20, v21
	v_max3_u32 v18, v18, v19, v20
	v_and_b32_e32 v19, 0x7fff, v8
	v_bfe_u32 v20, v8, 16, 15
	v_max_u32_e32 v19, v19, v20
	v_and_b32_e32 v20, 0x7fff, v9
	v_bfe_u32 v21, v9, 16, 15
	v_max_u32_e32 v20, v20, v21
	v_max3_u32 v18, v18, v19, v20
	s_waitcnt vmcnt(12)
	v_and_b32_e32 v19, 0x7fff, v2
	v_bfe_u32 v20, v2, 16, 15
	v_max_u32_e32 v19, v19, v20
	v_and_b32_e32 v20, 0x7fff, v3
	v_bfe_u32 v21, v3, 16, 15
	v_max_u32_e32 v20, v20, v21
	v_max3_u32 v18, v18, v19, v20
	v_and_b32_e32 v19, 0x7fff, v4
	v_bfe_u32 v20, v4, 16, 15
	v_max_u32_e32 v19, v19, v20
	v_and_b32_e32 v20, 0x7fff, v5
	v_bfe_u32 v21, v5, 16, 15
	v_max_u32_e32 v20, v20, v21
	v_max3_u32 v18, v18, v19, v20
	s_waitcnt lgkmcnt(0)
	s_nop 1
	v_max_u32_dpp v18, v18, v18 quad_perm:[1,0,3,2] row_mask:0xf bank_mask:0xf
	s_waitcnt lgkmcnt(0)
	s_nop 1
	v_max_u32_dpp v18, v18, v18 quad_perm:[2,3,0,1] row_mask:0xf bank_mask:0xf
	s_waitcnt lgkmcnt(0)
	s_nop 1
	v_max_u32_dpp v18, v18, v18 row_half_mirror row_mask:0xf bank_mask:0xf
	s_waitcnt lgkmcnt(0)
	s_nop 1
	v_max_u32_dpp v18, v18, v18 row_mirror row_mask:0xf bank_mask:0xf
	s_waitcnt lgkmcnt(0)
	v_mov_b32_e32 v19, v18
	s_nop 1
	v_permlane16_swap_b32_e32 v18, v19
	v_max_u32_e32 v18, v18, v19
	s_waitcnt lgkmcnt(0)
	v_mov_b32_e32 v19, v18
	s_nop 1
	v_permlane32_swap_b32_e32 v18, v19
	v_max_u32_e32 v19, v18, v19
	v_lshlrev_b32_e32 v18, 16, v19
	v_div_scale_f32 v20, s[8:9], v18, v18, s87
	v_rcp_f32_e32 v21, v20
	s_lshl_b64 s[8:9], s[16:17], 11
	v_fma_f32 v22, -v20, v21, 1.0
	v_fmac_f32_e32 v21, v22, v21
	v_div_scale_f32 v22, vcc, s87, v18, s87
	v_mul_f32_e32 v23, v22, v21
	v_fma_f32 v24, -v20, v23, v22
	v_fmac_f32_e32 v23, v24, v21
	v_fma_f32 v20, -v20, v23, v22
	v_div_fmas_f32 v20, v20, v21, v23
	v_div_fixup_f32 v20, v20, v18, s87
	v_cmp_ne_u32_e32 vcc, 0, v19
	v_lshlrev_b32_e32 v21, 16, v15
	v_and_b32_e32 v15, 0xffff0000, v15
	v_cndmask_b32_e32 v19, 0, v20, vcc
	v_lshlrev_b32_e32 v20, 16, v14
	v_and_b32_e32 v14, 0xffff0000, v14
	v_lshlrev_b32_e32 v22, 16, v16
	v_and_b32_e32 v16, 0xffff0000, v16
	v_lshlrev_b32_e32 v23, 16, v17
	v_and_b32_e32 v17, 0xffff0000, v17
	v_fmaak_f32 v20, v20, v19, 0x4b400000
	v_fmaak_f32 v14, v14, v19, 0x4b400000
	v_fmaak_f32 v21, v21, v19, 0x4b400000
	v_fmaak_f32 v15, v15, v19, 0x4b400000
	v_fmaak_f32 v22, v22, v19, 0x4b400000
	v_fmaak_f32 v16, v16, v19, 0x4b400000
	v_fmaak_f32 v23, v23, v19, 0x4b400000
	v_fmaak_f32 v17, v17, v19, 0x4b400000
	v_perm_b32 v14, v14, v20, s3
	v_perm_b32 v15, v15, v21, s33
	v_or_b32_e32 v14, v15, v14
	v_perm_b32 v15, v16, v22, s3
	v_perm_b32 v16, v17, v23, s33
	v_or_b32_e32 v15, v16, v15
	v_lshl_add_u64 v[16:17], v[68:69], 0, s[8:9]
	global_store_dwordx2 v[16:17], v[14:15], off
	v_lshlrev_b32_e32 v14, 16, v10
	v_and_b32_e32 v10, 0xffff0000, v10
	v_lshlrev_b32_e32 v15, 16, v11
	v_and_b32_e32 v11, 0xffff0000, v11
	v_lshlrev_b32_e32 v20, 16, v12
	v_and_b32_e32 v12, 0xffff0000, v12
	v_lshlrev_b32_e32 v21, 16, v13
	v_and_b32_e32 v13, 0xffff0000, v13
	v_fmaak_f32 v14, v14, v19, 0x4b400000
	v_fmaak_f32 v10, v10, v19, 0x4b400000
	v_fmaak_f32 v15, v15, v19, 0x4b400000
	v_fmaak_f32 v11, v11, v19, 0x4b400000
	v_fmaak_f32 v20, v20, v19, 0x4b400000
	v_fmaak_f32 v12, v12, v19, 0x4b400000
	v_fmaak_f32 v21, v21, v19, 0x4b400000
	v_fmaak_f32 v13, v13, v19, 0x4b400000
	v_perm_b32 v10, v10, v14, s3
	v_perm_b32 v11, v11, v15, s33
	v_or_b32_e32 v10, v11, v10
	v_perm_b32 v11, v12, v20, s3
	v_perm_b32 v12, v13, v21, s33
	v_or_b32_e32 v11, v12, v11
	global_store_dwordx2 v[16:17], v[10:11], off offset:512
	v_lshlrev_b32_e32 v10, 16, v6
	v_and_b32_e32 v6, 0xffff0000, v6
	v_lshlrev_b32_e32 v11, 16, v7
	v_and_b32_e32 v7, 0xffff0000, v7
	v_lshlrev_b32_e32 v12, 16, v8
	v_and_b32_e32 v8, 0xffff0000, v8
	v_lshlrev_b32_e32 v13, 16, v9
	v_and_b32_e32 v9, 0xffff0000, v9
	v_fmaak_f32 v10, v10, v19, 0x4b400000
	v_fmaak_f32 v6, v6, v19, 0x4b400000
	v_fmaak_f32 v11, v11, v19, 0x4b400000
	v_fmaak_f32 v7, v7, v19, 0x4b400000
	v_fmaak_f32 v12, v12, v19, 0x4b400000
	v_fmaak_f32 v8, v8, v19, 0x4b400000
	v_fmaak_f32 v13, v13, v19, 0x4b400000
	v_fmaak_f32 v9, v9, v19, 0x4b400000
	v_perm_b32 v6, v6, v10, s3
	v_perm_b32 v7, v7, v11, s33
	v_or_b32_e32 v6, v7, v6
	v_perm_b32 v7, v8, v12, s3
	v_perm_b32 v8, v9, v13, s33
	v_or_b32_e32 v7, v8, v7
	global_store_dwordx2 v[16:17], v[6:7], off offset:1024
	v_lshlrev_b32_e32 v6, 16, v2
	v_and_b32_e32 v2, 0xffff0000, v2
	v_lshlrev_b32_e32 v7, 16, v3
	v_and_b32_e32 v3, 0xffff0000, v3
	v_lshlrev_b32_e32 v8, 16, v4
	v_and_b32_e32 v4, 0xffff0000, v4
	v_lshlrev_b32_e32 v9, 16, v5
	v_and_b32_e32 v5, 0xffff0000, v5
	v_fmaak_f32 v6, v6, v19, 0x4b400000
	v_fmaak_f32 v2, v2, v19, 0x4b400000
	v_fmaak_f32 v7, v7, v19, 0x4b400000
	v_fmaak_f32 v3, v3, v19, 0x4b400000
	v_fmaak_f32 v8, v8, v19, 0x4b400000
	v_fmaak_f32 v4, v4, v19, 0x4b400000
	v_fmaak_f32 v9, v9, v19, 0x4b400000
	v_fmaak_f32 v5, v5, v19, 0x4b400000
	v_perm_b32 v2, v2, v6, s3
	v_perm_b32 v3, v3, v7, s33
	v_or_b32_e32 v2, v3, v2
	v_perm_b32 v3, v4, v8, s3
	v_perm_b32 v4, v5, v9, s33
	v_or_b32_e32 v3, v4, v3
	global_store_dwordx2 v[16:17], v[2:3], off offset:1536
	s_and_saveexec_b64 s[8:9], s[6:7]
	s_cbranch_execz .LBB0_130
	s_lshl_b64 s[16:17], s[16:17], 2
	s_add_u32 s16, s12, s16
	v_mul_f32_e32 v2, 0x3c010204, v18
	s_addc_u32 s17, s13, s17
	global_store_dword v163, v2, s[16:17]
	s_branch .LBB0_130

; __device__ __forceinline__ unsigned cvt_pk_bf16(float lo, float hi) { unsigned r; asm volatile("v_cvt_pk_bf16_f32 %0, %1, %2" : "=v"(r) : "v"(lo), "v"(hi)); return r; }
; __device__ __forceinline__ int v_rd_base(int lane) { return ((lane & 3) << 3) | (((lane >> 2) & 3) << 6) | (((lane >> 4) & 1) << 5) | (((lane >> 5) & 1) << 8); }
; __device__ __forceinline__ int crow(int r, int hi) { return (r & 3) + 8 * (r >> 2) + 4 * hi; }
; #define KV_STEP(KS) do { s16x4 al, ah, b0l, b0h, b1l, b1h; MX_RD(al, ah, vbV, 0, KS); MX_RD(b0l, b0h, vbK, 0, KS); MX_RD(b1l, b1h, vbK, 1, KS); MX_LWAIT(); \
;             c0 = MX_MFMA(MX_CAT(al, ah), MX_CAT(b0l, b0h), c0); c1 = MX_MFMA(MX_CAT(al, ah), MX_CAT(b1l, b1h), c1); } while (0)
; __device__ __forceinline__ void retkv_phase(const bf16_t* RK, const bf16_t* RV, bf16_t* kvT, lptr lds, int blk, int G, int tid_) {
;     ...
;         const int eb = wid & 3, db0 = 2 * (wid >> 2);
;         const int vbK = (int)(unsigned)(uintptr_t)lds + v_rd_base(lane) + db0 * 512, vbV = (int)(unsigned)(uintptr_t)lds + 16384 + v_rd_base(lane) + eb * 512;
;         f32x16 c0 = {}, c1 = {};
;     ...
;         KV_STEP(0); KV_STEP(1); KV_STEP(2); KV_STEP(3);
;     ...
;         bf16_t* op = kvT + ((size_t)unit << 14) + 32 * db0 + r32;
; #pragma unroll
;         for (int r = 0; r < 16; ++r) { const int e = 32 * eb + crow(r, hi); const float n0 = __shfl_xor(c0[r], 1), n1 = __shfl_xor(c1[r], 1);
;             if ((r32 & 1) == 0) { *(unsigned*)(op + e * 128) = cvt_pk_bf16(c0[r], n0); *(unsigned*)(op + e * 128 + 32) = cvt_pk_bf16(c1[r], n1); } }
.LBB0_569:
	s_waitcnt lgkmcnt(0)
	s_barrier
	ds_read_b64_tr_b16 v[2:3], v59 offset:0
	ds_read_b64_tr_b16 v[4:5], v59 offset:0x800
	ds_read_b64_tr_b16 v[6:7], v58 offset:0
	ds_read_b64_tr_b16 v[8:9], v58 offset:0x800
	ds_read_b64_tr_b16 v[10:11], v58 offset:0x200
	ds_read_b64_tr_b16 v[12:13], v58 offset:0xa00
	s_waitcnt lgkmcnt(0)
	ds_read_b64_tr_b16 v[64:65], v59 offset:0x1000
	s_nop 0
	v_mfma_f32_32x32x16_bf16 v[18:33], v[2:5], v[6:9], 0
	ds_read_b64_tr_b16 v[66:67], v59 offset:0x1800
	ds_read_b64_tr_b16 v[68:69], v58 offset:0x1000
	ds_read_b64_tr_b16 v[70:71], v58 offset:0x1800
	ds_read_b64_tr_b16 v[72:73], v58 offset:0x1200
	ds_read_b64_tr_b16 v[74:75], v58 offset:0x1a00
	s_waitcnt lgkmcnt(0)
	v_mfma_f32_32x32x16_bf16 v[2:17], v[2:5], v[10:13], 0
	v_mfma_f32_32x32x16_bf16 v[18:33], v[64:67], v[68:71], v[18:33]
	v_mfma_f32_32x32x16_bf16 v[2:17], v[64:67], v[72:75], v[2:17]
	ds_read_b64_tr_b16 v[64:65], v59 offset:0x2000
	ds_read_b64_tr_b16 v[66:67], v59 offset:0x2800
	ds_read_b64_tr_b16 v[68:69], v58 offset:0x2000
	ds_read_b64_tr_b16 v[70:71], v58 offset:0x2800
	ds_read_b64_tr_b16 v[72:73], v58 offset:0x2200
	ds_read_b64_tr_b16 v[74:75], v58 offset:0x2a00
	s_waitcnt lgkmcnt(0)
	s_nop 0
	v_mfma_f32_32x32x16_bf16 v[18:33], v[64:67], v[68:71], v[18:33]
	ds_read_b64_tr_b16 v[68:69], v59 offset:0x3000
	ds_read_b64_tr_b16 v[70:71], v59 offset:0x3800
	v_mfma_f32_32x32x16_bf16 v[2:17], v[64:67], v[72:75], v[2:17]
	ds_read_b64_tr_b16 v[64:65], v58 offset:0x3000
	ds_read_b64_tr_b16 v[66:67], v58 offset:0x3800
	ds_read_b64_tr_b16 v[72:73], v58 offset:0x3200
	ds_read_b64_tr_b16 v[74:75], v58 offset:0x3a00
	s_waitcnt lgkmcnt(0)
	s_nop 0
	v_mfma_f32_32x32x16_bf16 v[18:33], v[68:71], v[64:67], v[18:33]
	v_cmp_lt_i32_e32 vcc, v199, v198
	s_nop 1
	v_cndmask_b32_e32 v64, v195, v199, vcc
	v_lshlrev_b32_e32 v64, 2, v64
	s_nop 6
	s_nop 1
	v_mov_b32_dpp v66, v18 quad_perm:[1,0,3,2] row_mask:0xf bank_mask:0xf
	v_mfma_f32_32x32x16_bf16 v[2:17], v[68:71], v[72:75], v[2:17]
	s_nop 11
	s_nop 1
	v_mov_b32_dpp v65, v2 quad_perm:[1,0,3,2] row_mask:0xf bank_mask:0xf
	s_and_saveexec_b64 s[10:11], s[4:5]
	s_cbranch_execz .LBB0_571
	s_waitcnt lgkmcnt(1)
	v_cvt_pk_bf16_f32 v18, v18, v66
	global_store_dword v[56:57], v18, off
	s_waitcnt lgkmcnt(0)
	v_cvt_pk_bf16_f32 v2, v2, v65
	global_store_dword v[56:57], v2, off offset:64
.LBB0_571:
	s_or_b64 exec, exec, s[10:11]
	s_nop 1
	v_mov_b32_dpp v18, v19 quad_perm:[1,0,3,2] row_mask:0xf bank_mask:0xf
	v_mov_b32_dpp v2, v3 quad_perm:[1,0,3,2] row_mask:0xf bank_mask:0xf
	s_and_saveexec_b64 s[10:11], s[4:5]
	s_cbranch_execz .LBB0_573
	s_waitcnt lgkmcnt(1)
	v_cvt_pk_bf16_f32 v18, v19, v18
	global_store_dword v[56:57], v18, off offset:256
	s_waitcnt lgkmcnt(0)
	v_cvt_pk_bf16_f32 v2, v3, v2
	global_store_dword v[56:57], v2, off offset:320
.LBB0_573:
	s_or_b64 exec, exec, s[10:11]
	s_nop 1
	v_mov_b32_dpp v3, v20 quad_perm:[1,0,3,2] row_mask:0xf bank_mask:0xf
	s_waitcnt lgkmcnt(1)
	s_nop 1
	v_mov_b32_dpp v2, v4 quad_perm:[1,0,3,2] row_mask:0xf bank_mask:0xf
	s_and_saveexec_b64 s[10:11], s[4:5]
	s_cbranch_execz .LBB0_575
	s_waitcnt lgkmcnt(1)
	v_cvt_pk_bf16_f32 v3, v20, v3
	global_store_dword v[56:57], v3, off offset:512
	s_waitcnt lgkmcnt(0)
	v_cvt_pk_bf16_f32 v2, v4, v2
	global_store_dword v[56:57], v2, off offset:576
.LBB0_575:
	s_or_b64 exec, exec, s[10:11]
	s_waitcnt lgkmcnt(1)
	s_nop 1
	v_mov_b32_dpp v3, v21 quad_perm:[1,0,3,2] row_mask:0xf bank_mask:0xf
	s_waitcnt lgkmcnt(1)
	s_nop 1
	v_mov_b32_dpp v2, v5 quad_perm:[1,0,3,2] row_mask:0xf bank_mask:0xf
	s_and_saveexec_b64 s[10:11], s[4:5]
	s_cbranch_execz .LBB0_577
	s_waitcnt lgkmcnt(1)
	v_cvt_pk_bf16_f32 v3, v21, v3
	global_store_dword v[56:57], v3, off offset:768
	s_waitcnt lgkmcnt(0)
	v_cvt_pk_bf16_f32 v2, v5, v2
	global_store_dword v[56:57], v2, off offset:832
.LBB0_577:
	s_or_b64 exec, exec, s[10:11]
	s_waitcnt lgkmcnt(1)
	s_nop 1
	v_mov_b32_dpp v3, v22 quad_perm:[1,0,3,2] row_mask:0xf bank_mask:0xf
	s_waitcnt lgkmcnt(1)
	s_nop 1
	v_mov_b32_dpp v2, v6 quad_perm:[1,0,3,2] row_mask:0xf bank_mask:0xf
	s_and_saveexec_b64 s[10:11], s[4:5]
	s_cbranch_execz .LBB0_579
	s_waitcnt lgkmcnt(1)
	v_cvt_pk_bf16_f32 v3, v22, v3
	global_store_dword v[56:57], v3, off offset:2048
	s_waitcnt lgkmcnt(0)
	v_cvt_pk_bf16_f32 v2, v6, v2
	global_store_dword v[56:57], v2, off offset:2112
.LBB0_579:
	s_or_b64 exec, exec, s[10:11]
	s_waitcnt lgkmcnt(1)
	s_nop 1
	v_mov_b32_dpp v3, v23 quad_perm:[1,0,3,2] row_mask:0xf bank_mask:0xf
	s_waitcnt lgkmcnt(1)
	s_nop 1
	v_mov_b32_dpp v2, v7 quad_perm:[1,0,3,2] row_mask:0xf bank_mask:0xf
	s_and_saveexec_b64 s[10:11], s[4:5]
	s_cbranch_execz .LBB0_581
	s_waitcnt lgkmcnt(1)
	v_cvt_pk_bf16_f32 v3, v23, v3
	global_store_dword v[56:57], v3, off offset:2304
	s_waitcnt lgkmcnt(0)
	v_cvt_pk_bf16_f32 v2, v7, v2
	global_store_dword v[56:57], v2, off offset:2368
.LBB0_581:
	s_or_b64 exec, exec, s[10:11]
	s_waitcnt lgkmcnt(1)
	s_nop 1
	v_mov_b32_dpp v3, v24 quad_perm:[1,0,3,2] row_mask:0xf bank_mask:0xf
	s_waitcnt lgkmcnt(1)
	s_nop 1
	v_mov_b32_dpp v2, v8 quad_perm:[1,0,3,2] row_mask:0xf bank_mask:0xf
	s_and_saveexec_b64 s[10:11], s[4:5]
	s_cbranch_execz .LBB0_583
	s_waitcnt lgkmcnt(1)
	v_cvt_pk_bf16_f32 v3, v24, v3
	global_store_dword v[56:57], v3, off offset:2560
	s_waitcnt lgkmcnt(0)
	v_cvt_pk_bf16_f32 v2, v8, v2
	global_store_dword v[56:57], v2, off offset:2624
; __device__ __forceinline__ unsigned cvt_pk_bf16(float lo, float hi) { unsigned r; asm volatile("v_cvt_pk_bf16_f32 %0, %1, %2" : "=v"(r) : "v"(lo), "v"(hi)); return r; }
; __device__ __forceinline__ int crow(int r, int hi) { return (r & 3) + 8 * (r >> 2) + 4 * hi; }
; __device__ __forceinline__ void retkv_phase(const bf16_t* RK, const bf16_t* RV, bf16_t* kvT, lptr lds, int blk, int G, int tid_) {
;     ...
;         bf16_t* op = kvT + ((size_t)unit << 14) + 32 * db0 + r32;
; #pragma unroll
;         for (int r = 0; r < 16; ++r) { const int e = 32 * eb + crow(r, hi); const float n0 = __shfl_xor(c0[r], 1), n1 = __shfl_xor(c1[r], 1);
;             if ((r32 & 1) == 0) { *(unsigned*)(op + e * 128) = cvt_pk_bf16(c0[r], n0); *(unsigned*)(op + e * 128 + 32) = cvt_pk_bf16(c1[r], n1); } }
.LBB0_583:
	s_or_b64 exec, exec, s[10:11]
	s_waitcnt lgkmcnt(1)
	s_nop 1
	v_mov_b32_dpp v3, v25 quad_perm:[1,0,3,2] row_mask:0xf bank_mask:0xf
	s_waitcnt lgkmcnt(1)
	s_nop 1
	v_mov_b32_dpp v2, v9 quad_perm:[1,0,3,2] row_mask:0xf bank_mask:0xf
	s_and_saveexec_b64 s[10:11], s[4:5]
	s_cbranch_execz .LBB0_585
	s_waitcnt lgkmcnt(1)
	v_cvt_pk_bf16_f32 v3, v25, v3
	global_store_dword v[56:57], v3, off offset:2816
	s_waitcnt lgkmcnt(0)
	v_cvt_pk_bf16_f32 v2, v9, v2
	global_store_dword v[56:57], v2, off offset:2880
.LBB0_585:
	s_or_b64 exec, exec, s[10:11]
	s_waitcnt lgkmcnt(1)
	s_nop 1
	v_mov_b32_dpp v3, v26 quad_perm:[1,0,3,2] row_mask:0xf bank_mask:0xf
	s_waitcnt lgkmcnt(1)
	s_nop 1
	v_mov_b32_dpp v2, v10 quad_perm:[1,0,3,2] row_mask:0xf bank_mask:0xf
	s_and_saveexec_b64 s[10:11], s[4:5]
	s_cbranch_execz .LBB0_587
	v_add_co_u32_e32 v4, vcc, 0x1000, v56
	s_waitcnt lgkmcnt(1)
	v_cvt_pk_bf16_f32 v3, v26, v3
	s_nop 0
	v_addc_co_u32_e32 v5, vcc, 0, v57, vcc
	global_store_dword v[4:5], v3, off
	s_waitcnt lgkmcnt(0)
	v_cvt_pk_bf16_f32 v2, v10, v2
	global_store_dword v[4:5], v2, off offset:64
.LBB0_587:
	s_or_b64 exec, exec, s[10:11]
	s_waitcnt lgkmcnt(1)
	s_nop 1
	v_mov_b32_dpp v3, v27 quad_perm:[1,0,3,2] row_mask:0xf bank_mask:0xf
	s_waitcnt lgkmcnt(1)
	s_nop 1
	v_mov_b32_dpp v2, v11 quad_perm:[1,0,3,2] row_mask:0xf bank_mask:0xf
	s_and_saveexec_b64 s[10:11], s[4:5]
	s_cbranch_execz .LBB0_589
	v_add_co_u32_e32 v4, vcc, 0x1000, v56
	s_waitcnt lgkmcnt(1)
	v_cvt_pk_bf16_f32 v3, v27, v3
	s_nop 0
	v_addc_co_u32_e32 v5, vcc, 0, v57, vcc
	global_store_dword v[4:5], v3, off offset:256
	s_waitcnt lgkmcnt(0)
	v_cvt_pk_bf16_f32 v2, v11, v2
	global_store_dword v[4:5], v2, off offset:320
.LBB0_589:
	s_or_b64 exec, exec, s[10:11]
	s_waitcnt lgkmcnt(1)
	s_nop 1
	v_mov_b32_dpp v3, v28 quad_perm:[1,0,3,2] row_mask:0xf bank_mask:0xf
	s_waitcnt lgkmcnt(1)
	s_nop 1
	v_mov_b32_dpp v2, v12 quad_perm:[1,0,3,2] row_mask:0xf bank_mask:0xf
	s_and_saveexec_b64 s[10:11], s[4:5]
	s_cbranch_execz .LBB0_591
	v_add_co_u32_e32 v4, vcc, 0x1000, v56
	s_waitcnt lgkmcnt(1)
	v_cvt_pk_bf16_f32 v3, v28, v3
	s_nop 0
	v_addc_co_u32_e32 v5, vcc, 0, v57, vcc
	global_store_dword v[4:5], v3, off offset:512
	s_waitcnt lgkmcnt(0)
	v_cvt_pk_bf16_f32 v2, v12, v2
	global_store_dword v[4:5], v2, off offset:576
.LBB0_591:
	s_or_b64 exec, exec, s[10:11]
	s_waitcnt lgkmcnt(1)
	s_nop 1
	v_mov_b32_dpp v3, v29 quad_perm:[1,0,3,2] row_mask:0xf bank_mask:0xf
	s_waitcnt lgkmcnt(1)
	s_nop 1
	v_mov_b32_dpp v2, v13 quad_perm:[1,0,3,2] row_mask:0xf bank_mask:0xf
	s_and_saveexec_b64 s[10:11], s[4:5]
	s_cbranch_execz .LBB0_593
	v_add_co_u32_e32 v4, vcc, 0x1000, v56
	s_waitcnt lgkmcnt(1)
	v_cvt_pk_bf16_f32 v3, v29, v3
	s_nop 0
	v_addc_co_u32_e32 v5, vcc, 0, v57, vcc
	global_store_dword v[4:5], v3, off offset:768
	s_waitcnt lgkmcnt(0)
	v_cvt_pk_bf16_f32 v2, v13, v2
	global_store_dword v[4:5], v2, off offset:832
.LBB0_593:
	s_or_b64 exec, exec, s[10:11]
	s_waitcnt lgkmcnt(1)
	s_nop 1
	v_mov_b32_dpp v3, v30 quad_perm:[1,0,3,2] row_mask:0xf bank_mask:0xf
	s_waitcnt lgkmcnt(1)
	s_nop 1
	v_mov_b32_dpp v2, v14 quad_perm:[1,0,3,2] row_mask:0xf bank_mask:0xf
	s_and_saveexec_b64 s[10:11], s[4:5]
	s_cbranch_execz .LBB0_595
	v_add_co_u32_e32 v4, vcc, 0x1000, v56
	s_waitcnt lgkmcnt(1)
	v_cvt_pk_bf16_f32 v3, v30, v3
	s_nop 0
	v_addc_co_u32_e32 v5, vcc, 0, v57, vcc
	global_store_dword v[4:5], v3, off offset:2048
	s_waitcnt lgkmcnt(0)
	v_cvt_pk_bf16_f32 v2, v14, v2
	global_store_dword v[4:5], v2, off offset:2112
.LBB0_595:
	s_or_b64 exec, exec, s[10:11]
	s_waitcnt lgkmcnt(1)
	s_nop 1
	v_mov_b32_dpp v3, v31 quad_perm:[1,0,3,2] row_mask:0xf bank_mask:0xf
	s_waitcnt lgkmcnt(1)
	s_nop 1
	v_mov_b32_dpp v2, v15 quad_perm:[1,0,3,2] row_mask:0xf bank_mask:0xf
	s_and_saveexec_b64 s[10:11], s[4:5]
	s_cbranch_execz .LBB0_597
	v_add_co_u32_e32 v4, vcc, 0x1000, v56
	s_waitcnt lgkmcnt(1)
	v_cvt_pk_bf16_f32 v3, v31, v3
	s_nop 0
	v_addc_co_u32_e32 v5, vcc, 0, v57, vcc
	global_store_dword v[4:5], v3, off offset:2304
	s_waitcnt lgkmcnt(0)
	v_cvt_pk_bf16_f32 v2, v15, v2
	global_store_dword v[4:5], v2, off offset:2368
.LBB0_597:
	s_or_b64 exec, exec, s[10:11]
	s_waitcnt lgkmcnt(1)
	s_nop 1
	v_mov_b32_dpp v3, v32 quad_perm:[1,0,3,2] row_mask:0xf bank_mask:0xf
	s_waitcnt lgkmcnt(1)
	s_nop 1
	v_mov_b32_dpp v2, v16 quad_perm:[1,0,3,2] row_mask:0xf bank_mask:0xf
	s_and_saveexec_b64 s[10:11], s[4:5]
	s_cbranch_execz .LBB0_599
	v_add_co_u32_e32 v4, vcc, 0x1000, v56
	s_waitcnt lgkmcnt(1)
	v_cvt_pk_bf16_f32 v3, v32, v3
	s_nop 0
	v_addc_co_u32_e32 v5, vcc, 0, v57, vcc
	global_store_dword v[4:5], v3, off offset:2560
	s_waitcnt lgkmcnt(0)
	v_cvt_pk_bf16_f32 v2, v16, v2
	global_store_dword v[4:5], v2, off offset:2624
.LBB0_599:
	s_or_b64 exec, exec, s[10:11]
	s_waitcnt lgkmcnt(1)
	s_nop 1
	v_mov_b32_dpp v3, v33 quad_perm:[1,0,3,2] row_mask:0xf bank_mask:0xf
	s_waitcnt lgkmcnt(1)
	s_nop 1
	v_mov_b32_dpp v2, v17 quad_perm:[1,0,3,2] row_mask:0xf bank_mask:0xf
	s_and_saveexec_b64 s[10:11], s[4:5]
	s_cbranch_execz .LBB0_566
	v_add_co_u32_e32 v4, vcc, 0x1000, v56
	s_waitcnt lgkmcnt(1)
	v_cvt_pk_bf16_f32 v3, v33, v3
	s_nop 0
	v_addc_co_u32_e32 v5, vcc, 0, v57, vcc
	global_store_dword v[4:5], v3, off offset:2816
	s_waitcnt lgkmcnt(0)
	v_cvt_pk_bf16_f32 v2, v17, v2
	global_store_dword v[4:5], v2, off offset:2880
	s_branch .LBB0_566

; __device__ __forceinline__ void quant_rows(const bf16_t* xb, unsigned char* xq, float* qs, const float* ssq, unsigned* cnt, int pm, int quarter, LAS float* rsl, int tid_) {
;     ...
; #pragma unroll
;         for (int q = 0; q < 4; ++q)
; #pragma unroll
;             for (int j = 0; j < 4; ++j) v[q][j] = *(const u32x4*)(xb + (size_t)(rbase + q) * DM + (j * 64 + lane) * 8);
; #pragma unroll
;         for (int q = 0; q < 4; ++q) {
;             unsigned mx = 0u;
; #pragma unroll
;             for (int j = 0; j < 4; ++j)
; #pragma unroll
;                 for (int e = 0; e < 4; ++e) { const unsigned w = v[q][j][e]; mx = max(mx, max(w & 0x7fffu, (w >> 16) & 0x7fffu)); }
; #pragma unroll
;             for (int o = 1; o < 64; o <<= 1) mx = max(mx, (unsigned)__shfl_xor((int)mx, o));
;             const float amax = __uint_as_float(mx << 16);
;             const float inv = mx ? 127.0f / amax : 0.f;
; #pragma unroll
;             for (int j = 0; j < 4; ++j) { float f[8]; unpack8(v[q][j], f); unsigned b[8];
; #pragma unroll
;                 for (int e = 0; e < 8; ++e) b[e] = __float_as_uint(__builtin_fmaf(f[e], inv, QMAGIC));
;                 u32x2 o; o.x = pack4q(b[0], b[1], b[2], b[3]); o.y = pack4q(b[4], b[5], b[6], b[7]);
;                 *(u32x2*)(xq + (size_t)(rbase + q) * DM + (j * 64 + lane) * 8) = o; }
;             if (lane == 0) qs[rbase + q] = amax * (1.0f / 127.0f);
.LBB0_1107:
	s_or_b32 s20, s14, s25
	s_ashr_i32 s21, s20, 31
	s_lshl_b64 s[14:15], s[20:21], 12
	v_lshl_add_u64 v[2:3], v[66:67], 0, s[14:15]
	global_load_dwordx4 v[62:65], v[2:3], off
	global_load_dwordx4 v[58:61], v[2:3], off offset:1024
	global_load_dwordx4 v[54:57], v[2:3], off offset:2048
	global_load_dwordx4 v[50:53], v[2:3], off offset:3072
	s_or_b32 s18, s20, 1
	s_ashr_i32 s19, s18, 31
	s_or_b32 s16, s20, 2
	s_lshl_b64 s[14:15], s[18:19], 12
	s_ashr_i32 s17, s16, 31
	v_lshl_add_u64 v[2:3], v[66:67], 0, s[14:15]
	s_lshl_b64 s[14:15], s[16:17], 12
	global_load_dwordx4 v[46:49], v[2:3], off
	global_load_dwordx4 v[42:45], v[2:3], off offset:1024
	global_load_dwordx4 v[38:41], v[2:3], off offset:2048
	global_load_dwordx4 v[34:37], v[2:3], off offset:3072
	v_lshl_add_u64 v[2:3], v[66:67], 0, s[14:15]
	s_or_b32 s14, s20, 3
	s_ashr_i32 s15, s14, 31
	s_lshl_b64 s[22:23], s[14:15], 12
	global_load_dwordx4 v[30:33], v[2:3], off
	global_load_dwordx4 v[26:29], v[2:3], off offset:1024
	global_load_dwordx4 v[22:25], v[2:3], off offset:2048
	global_load_dwordx4 v[18:21], v[2:3], off offset:3072
	v_lshl_add_u64 v[2:3], v[66:67], 0, s[22:23]
	global_load_dwordx4 v[14:17], v[2:3], off
	global_load_dwordx4 v[10:13], v[2:3], off offset:1024
	global_load_dwordx4 v[6:9], v[2:3], off offset:2048
	s_nop 0
	global_load_dwordx4 v[2:5], v[2:3], off offset:3072
	s_waitcnt vmcnt(0)
	v_and_b32_e32 v79, 0x7fff, v63
	v_bfe_u32 v80, v63, 16, 15
	v_and_b32_e32 v77, 0x7fff, v62
	v_bfe_u32 v78, v62, 16, 15
	v_max_u32_e32 v79, v79, v80
	v_max3_u32 v77, v77, v78, v79
	v_and_b32_e32 v78, 0x7fff, v64
	v_bfe_u32 v79, v64, 16, 15
	v_max_u32_e32 v78, v78, v79
	v_and_b32_e32 v79, 0x7fff, v65
	v_bfe_u32 v80, v65, 16, 15
	v_max_u32_e32 v79, v79, v80
	v_max3_u32 v77, v77, v78, v79
	v_and_b32_e32 v78, 0x7fff, v58
	v_bfe_u32 v79, v58, 16, 15
	v_max_u32_e32 v78, v78, v79
	v_and_b32_e32 v79, 0x7fff, v59
	v_bfe_u32 v80, v59, 16, 15
	v_max_u32_e32 v79, v79, v80
	v_max3_u32 v77, v77, v78, v79
	v_and_b32_e32 v78, 0x7fff, v60
	v_bfe_u32 v79, v60, 16, 15
	v_max_u32_e32 v78, v78, v79
	v_and_b32_e32 v79, 0x7fff, v61
	v_bfe_u32 v80, v61, 16, 15
	v_max_u32_e32 v79, v79, v80
	v_max3_u32 v77, v77, v78, v79
	v_and_b32_e32 v78, 0x7fff, v54
	v_bfe_u32 v79, v54, 16, 15
	v_max_u32_e32 v78, v78, v79
	v_and_b32_e32 v79, 0x7fff, v55
	v_bfe_u32 v80, v55, 16, 15
	v_max_u32_e32 v79, v79, v80
	v_max3_u32 v77, v77, v78, v79
	v_and_b32_e32 v78, 0x7fff, v56
	v_bfe_u32 v79, v56, 16, 15
	v_max_u32_e32 v78, v78, v79
	v_and_b32_e32 v79, 0x7fff, v57
	v_bfe_u32 v80, v57, 16, 15
	v_max_u32_e32 v79, v79, v80
	v_max3_u32 v77, v77, v78, v79
	v_and_b32_e32 v78, 0x7fff, v50
	v_bfe_u32 v79, v50, 16, 15
	v_max_u32_e32 v78, v78, v79
	v_and_b32_e32 v79, 0x7fff, v51
	v_bfe_u32 v80, v51, 16, 15
	v_max_u32_e32 v79, v79, v80
	v_max3_u32 v77, v77, v78, v79
	v_and_b32_e32 v78, 0x7fff, v52
	v_bfe_u32 v79, v52, 16, 15
	v_max_u32_e32 v78, v78, v79
	v_and_b32_e32 v79, 0x7fff, v53
	v_bfe_u32 v80, v53, 16, 15
	v_max_u32_e32 v79, v79, v80
	v_max3_u32 v77, v77, v78, v79
	s_waitcnt lgkmcnt(0)
	s_nop 1
	v_max_u32_dpp v77, v77, v77 quad_perm:[1,0,3,2] row_mask:0xf bank_mask:0xf
	s_waitcnt lgkmcnt(0)
	s_nop 1
	v_max_u32_dpp v77, v77, v77 quad_perm:[2,3,0,1] row_mask:0xf bank_mask:0xf
	s_waitcnt lgkmcnt(0)
	s_nop 1
	v_max_u32_dpp v77, v77, v77 row_half_mirror row_mask:0xf bank_mask:0xf
	s_waitcnt lgkmcnt(0)
	s_nop 1
	v_max_u32_dpp v77, v77, v77 row_mirror row_mask:0xf bank_mask:0xf
	s_waitcnt lgkmcnt(0)
	v_mov_b32_e32 v78, v77
	s_nop 1
	v_permlane16_swap_b32_e32 v77, v78
	v_max_u32_e32 v77, v77, v78
	s_waitcnt lgkmcnt(0)
	v_mov_b32_e32 v78, v77
	s_nop 1
	v_permlane32_swap_b32_e32 v77, v78
	v_max_u32_e32 v78, v77, v78
	v_lshlrev_b32_e32 v77, 16, v78
	v_div_scale_f32 v79, s[22:23], v77, v77, s87
	v_rcp_f32_e32 v80, v79
	s_lshl_b64 s[22:23], s[20:21], 11
	v_fma_f32 v81, -v79, v80, 1.0
	v_fmac_f32_e32 v80, v81, v80
	v_div_scale_f32 v81, vcc, s87, v77, s87
	v_mul_f32_e32 v82, v81, v80
	v_fma_f32 v83, -v79, v82, v81
	v_fmac_f32_e32 v82, v83, v80
	v_fma_f32 v79, -v79, v82, v81
	v_div_fmas_f32 v79, v79, v80, v82
	v_div_fixup_f32 v79, v79, v77, s87
	v_cmp_ne_u32_e32 vcc, 0, v78
	v_lshlrev_b32_e32 v80, 16, v63
	v_and_b32_e32 v63, 0xffff0000, v63
	v_cndmask_b32_e32 v78, 0, v79, vcc
	v_lshlrev_b32_e32 v79, 16, v62
	v_and_b32_e32 v62, 0xffff0000, v62
	v_lshlrev_b32_e32 v81, 16, v64
	v_and_b32_e32 v64, 0xffff0000, v64
	v_lshlrev_b32_e32 v82, 16, v65
	v_and_b32_e32 v65, 0xffff0000, v65
	v_fmaak_f32 v79, v79, v78, 0x4b400000
	v_fmaak_f32 v62, v62, v78, 0x4b400000
	v_fmaak_f32 v80, v80, v78, 0x4b400000
	v_fmaak_f32 v63, v63, v78, 0x4b400000
	v_fmaak_f32 v81, v81, v78, 0x4b400000
	v_fmaak_f32 v83, v64, v78, 0x4b400000
	v_fmaak_f32 v82, v82, v78, 0x4b400000
	v_fmaak_f32 v65, v65, v78, 0x4b400000
	v_perm_b32 v62, v62, v79, s3
	v_perm_b32 v63, v63, v80, s33
	v_or_b32_e32 v64, v63, v62
	v_perm_b32 v62, v83, v81, s3
	v_perm_b32 v63, v65, v82, s33
	v_or_b32_e32 v65, v63, v62
	v_lshl_add_u64 v[62:63], v[68:69], 0, s[22:23]
	global_store_dwordx2 v[62:63], v[64:65], off
	v_lshlrev_b32_e32 v64, 16, v58
	v_and_b32_e32 v58, 0xffff0000, v58
	v_lshlrev_b32_e32 v65, 16, v59
	v_and_b32_e32 v59, 0xffff0000, v59
	v_lshlrev_b32_e32 v79, 16, v60
	v_and_b32_e32 v60, 0xffff0000, v60
	v_lshlrev_b32_e32 v80, 16, v61
	v_and_b32_e32 v61, 0xffff0000, v61
	v_fmaak_f32 v64, v64, v78, 0x4b400000
	v_fmaak_f32 v58, v58, v78, 0x4b400000
	v_fmaak_f32 v65, v65, v78, 0x4b400000
	v_fmaak_f32 v59, v59, v78, 0x4b400000
	v_fmaak_f32 v79, v79, v78, 0x4b400000
	v_fmaak_f32 v60, v60, v78, 0x4b400000
	v_fmaak_f32 v80, v80, v78, 0x4b400000
	v_fmaak_f32 v61, v61, v78, 0x4b400000
	v_perm_b32 v58, v58, v64, s3
; __device__ __forceinline__ void quant_rows(const bf16_t* xb, unsigned char* xq, float* qs, const float* ssq, unsigned* cnt, int pm, int quarter, LAS float* rsl, int tid_) {
;     ...
;         for (int q = 0; q < 4; ++q) {
;             unsigned mx = 0u;
; #pragma unroll
;             for (int j = 0; j < 4; ++j)
; #pragma unroll
;                 for (int e = 0; e < 4; ++e) { const unsigned w = v[q][j][e]; mx = max(mx, max(w & 0x7fffu, (w >> 16) & 0x7fffu)); }
; #pragma unroll
;             for (int o = 1; o < 64; o <<= 1) mx = max(mx, (unsigned)__shfl_xor((int)mx, o));
;             const float amax = __uint_as_float(mx << 16);
;             const float inv = mx ? 127.0f / amax : 0.f;
; #pragma unroll
;             for (int j = 0; j < 4; ++j) { float f[8]; unpack8(v[q][j], f); unsigned b[8];
; #pragma unroll
;                 for (int e = 0; e < 8; ++e) b[e] = __float_as_uint(__builtin_fmaf(f[e], inv, QMAGIC));
;                 u32x2 o; o.x = pack4q(b[0], b[1], b[2], b[3]); o.y = pack4q(b[4], b[5], b[6], b[7]);
;                 *(u32x2*)(xq + (size_t)(rbase + q) * DM + (j * 64 + lane) * 8) = o; }
;             if (lane == 0) qs[rbase + q] = amax * (1.0f / 127.0f);
	v_perm_b32 v59, v59, v65, s33
	v_or_b32_e32 v58, v59, v58
	v_perm_b32 v59, v60, v79, s3
	v_perm_b32 v60, v61, v80, s33
	v_or_b32_e32 v59, v60, v59
	global_store_dwordx2 v[62:63], v[58:59], off offset:512
	v_lshlrev_b32_e32 v58, 16, v54
	v_and_b32_e32 v54, 0xffff0000, v54
	v_lshlrev_b32_e32 v59, 16, v55
	v_and_b32_e32 v55, 0xffff0000, v55
	v_lshlrev_b32_e32 v60, 16, v56
	v_and_b32_e32 v56, 0xffff0000, v56
	v_lshlrev_b32_e32 v61, 16, v57
	v_and_b32_e32 v57, 0xffff0000, v57
	v_fmaak_f32 v58, v58, v78, 0x4b400000
	v_fmaak_f32 v54, v54, v78, 0x4b400000
	v_fmaak_f32 v59, v59, v78, 0x4b400000
	v_fmaak_f32 v55, v55, v78, 0x4b400000
	v_fmaak_f32 v60, v60, v78, 0x4b400000
	v_fmaak_f32 v56, v56, v78, 0x4b400000
	v_fmaak_f32 v61, v61, v78, 0x4b400000
	v_fmaak_f32 v57, v57, v78, 0x4b400000
	v_perm_b32 v54, v54, v58, s3
	v_perm_b32 v55, v55, v59, s33
	v_or_b32_e32 v54, v55, v54
	v_perm_b32 v55, v56, v60, s3
	v_perm_b32 v56, v57, v61, s33
	v_or_b32_e32 v55, v56, v55
	global_store_dwordx2 v[62:63], v[54:55], off offset:1024
	v_lshlrev_b32_e32 v54, 16, v50
	v_and_b32_e32 v50, 0xffff0000, v50
	v_lshlrev_b32_e32 v55, 16, v51
	v_and_b32_e32 v51, 0xffff0000, v51
	v_lshlrev_b32_e32 v56, 16, v52
	v_and_b32_e32 v52, 0xffff0000, v52
	v_lshlrev_b32_e32 v57, 16, v53
	v_and_b32_e32 v53, 0xffff0000, v53
	v_fmaak_f32 v54, v54, v78, 0x4b400000
	v_fmaak_f32 v50, v50, v78, 0x4b400000
	v_fmaak_f32 v55, v55, v78, 0x4b400000
	v_fmaak_f32 v51, v51, v78, 0x4b400000
	v_fmaak_f32 v56, v56, v78, 0x4b400000
	v_fmaak_f32 v52, v52, v78, 0x4b400000
	v_fmaak_f32 v57, v57, v78, 0x4b400000
	v_fmaak_f32 v53, v53, v78, 0x4b400000
	v_perm_b32 v50, v50, v54, s3
	v_perm_b32 v51, v51, v55, s33
	v_or_b32_e32 v50, v51, v50
	v_perm_b32 v51, v52, v56, s3
	v_perm_b32 v52, v53, v57, s33
	v_or_b32_e32 v51, v52, v51
	global_store_dwordx2 v[62:63], v[50:51], off offset:1536
	s_and_saveexec_b64 s[22:23], s[6:7]
	s_cbranch_execz .LBB0_1109
	s_lshl_b64 s[20:21], s[20:21], 2
	s_add_u32 s20, s8, s20
	v_mul_f32_e32 v50, 0x3c010204, v77
	s_addc_u32 s21, s9, s21
	global_store_dword v163, v50, s[20:21]
.LBB0_1109:
	s_or_b64 exec, exec, s[22:23]
	v_and_b32_e32 v52, 0x7fff, v47
	v_bfe_u32 v53, v47, 16, 15
	v_and_b32_e32 v50, 0x7fff, v46
	v_bfe_u32 v51, v46, 16, 15
	v_max_u32_e32 v52, v52, v53
	v_max3_u32 v50, v50, v51, v52
	v_and_b32_e32 v51, 0x7fff, v48
	v_bfe_u32 v52, v48, 16, 15
	v_max_u32_e32 v51, v51, v52
	v_and_b32_e32 v52, 0x7fff, v49
	v_bfe_u32 v53, v49, 16, 15
	v_max_u32_e32 v52, v52, v53
	v_max3_u32 v50, v50, v51, v52
	v_and_b32_e32 v51, 0x7fff, v42
	v_bfe_u32 v52, v42, 16, 15
	v_max_u32_e32 v51, v51, v52
	v_and_b32_e32 v52, 0x7fff, v43
	v_bfe_u32 v53, v43, 16, 15
	v_max_u32_e32 v52, v52, v53
	v_max3_u32 v50, v50, v51, v52
	v_and_b32_e32 v51, 0x7fff, v44
	v_bfe_u32 v52, v44, 16, 15
	v_max_u32_e32 v51, v51, v52
	v_and_b32_e32 v52, 0x7fff, v45
	v_bfe_u32 v53, v45, 16, 15
	v_max_u32_e32 v52, v52, v53
	v_max3_u32 v50, v50, v51, v52
	v_and_b32_e32 v51, 0x7fff, v38
	v_bfe_u32 v52, v38, 16, 15
	v_max_u32_e32 v51, v51, v52
	v_and_b32_e32 v52, 0x7fff, v39
	v_bfe_u32 v53, v39, 16, 15
	v_max_u32_e32 v52, v52, v53
	v_max3_u32 v50, v50, v51, v52
	v_and_b32_e32 v51, 0x7fff, v40
	v_bfe_u32 v52, v40, 16, 15
	v_max_u32_e32 v51, v51, v52
	v_and_b32_e32 v52, 0x7fff, v41
	v_bfe_u32 v53, v41, 16, 15
	v_max_u32_e32 v52, v52, v53
	v_max3_u32 v50, v50, v51, v52
	v_and_b32_e32 v51, 0x7fff, v34
	v_bfe_u32 v52, v34, 16, 15
	v_max_u32_e32 v51, v51, v52
	v_and_b32_e32 v52, 0x7fff, v35
	v_bfe_u32 v53, v35, 16, 15
	v_max_u32_e32 v52, v52, v53
	v_max3_u32 v50, v50, v51, v52
	v_and_b32_e32 v51, 0x7fff, v36
	v_bfe_u32 v52, v36, 16, 15
	v_max_u32_e32 v51, v51, v52
	v_and_b32_e32 v52, 0x7fff, v37
	v_bfe_u32 v53, v37, 16, 15
	v_max_u32_e32 v52, v52, v53
	v_max3_u32 v50, v50, v51, v52
	s_waitcnt lgkmcnt(0)
	s_nop 1
	v_max_u32_dpp v50, v50, v50 quad_perm:[1,0,3,2] row_mask:0xf bank_mask:0xf
	s_waitcnt lgkmcnt(0)
	s_nop 1
	v_max_u32_dpp v50, v50, v50 quad_perm:[2,3,0,1] row_mask:0xf bank_mask:0xf
	s_waitcnt lgkmcnt(0)
	s_nop 1
	v_max_u32_dpp v50, v50, v50 row_half_mirror row_mask:0xf bank_mask:0xf
	s_waitcnt lgkmcnt(0)
	s_nop 1
	v_max_u32_dpp v50, v50, v50 row_mirror row_mask:0xf bank_mask:0xf
	s_waitcnt lgkmcnt(0)
	v_mov_b32_e32 v51, v50
	s_nop 1
	v_permlane16_swap_b32_e32 v50, v51
	v_max_u32_e32 v50, v50, v51
	s_waitcnt lgkmcnt(0)
; __device__ __forceinline__ void quant_rows(const bf16_t* xb, unsigned char* xq, float* qs, const float* ssq, unsigned* cnt, int pm, int quarter, LAS float* rsl, int tid_) {
;     ...
;         for (int q = 0; q < 4; ++q) {
;             unsigned mx = 0u;
; #pragma unroll
;             for (int j = 0; j < 4; ++j)
; #pragma unroll
;                 for (int e = 0; e < 4; ++e) { const unsigned w = v[q][j][e]; mx = max(mx, max(w & 0x7fffu, (w >> 16) & 0x7fffu)); }
; #pragma unroll
;             for (int o = 1; o < 64; o <<= 1) mx = max(mx, (unsigned)__shfl_xor((int)mx, o));
;             const float amax = __uint_as_float(mx << 16);
;             const float inv = mx ? 127.0f / amax : 0.f;
; #pragma unroll
;             for (int j = 0; j < 4; ++j) { float f[8]; unpack8(v[q][j], f); unsigned b[8];
; #pragma unroll
;                 for (int e = 0; e < 8; ++e) b[e] = __float_as_uint(__builtin_fmaf(f[e], inv, QMAGIC));
;                 u32x2 o; o.x = pack4q(b[0], b[1], b[2], b[3]); o.y = pack4q(b[4], b[5], b[6], b[7]);
;                 *(u32x2*)(xq + (size_t)(rbase + q) * DM + (j * 64 + lane) * 8) = o; }
;             if (lane == 0) qs[rbase + q] = amax * (1.0f / 127.0f);
	v_mov_b32_e32 v51, v50
	s_nop 1
	v_permlane32_swap_b32_e32 v50, v51
	v_max_u32_e32 v51, v50, v51
	v_lshlrev_b32_e32 v50, 16, v51
	v_div_scale_f32 v52, s[20:21], v50, v50, s87
	v_rcp_f32_e32 v53, v52
	s_lshl_b64 s[20:21], s[18:19], 11
	v_fma_f32 v54, -v52, v53, 1.0
	v_fmac_f32_e32 v53, v54, v53
	v_div_scale_f32 v54, vcc, s87, v50, s87
	v_mul_f32_e32 v55, v54, v53
	v_fma_f32 v56, -v52, v55, v54
	v_fmac_f32_e32 v55, v56, v53
	v_fma_f32 v52, -v52, v55, v54
	v_div_fmas_f32 v52, v52, v53, v55
	v_div_fixup_f32 v52, v52, v50, s87
	v_cmp_ne_u32_e32 vcc, 0, v51
	v_lshlrev_b32_e32 v53, 16, v47
	v_and_b32_e32 v47, 0xffff0000, v47
	v_cndmask_b32_e32 v51, 0, v52, vcc
	v_lshlrev_b32_e32 v52, 16, v46
	v_and_b32_e32 v46, 0xffff0000, v46
	v_lshlrev_b32_e32 v54, 16, v48
	v_and_b32_e32 v48, 0xffff0000, v48
	v_lshlrev_b32_e32 v55, 16, v49
	v_and_b32_e32 v49, 0xffff0000, v49
	v_fmaak_f32 v52, v52, v51, 0x4b400000
	v_fmaak_f32 v46, v46, v51, 0x4b400000
	v_fmaak_f32 v53, v53, v51, 0x4b400000
	v_fmaak_f32 v47, v47, v51, 0x4b400000
	v_fmaak_f32 v54, v54, v51, 0x4b400000
	v_fmaak_f32 v48, v48, v51, 0x4b400000
	v_fmaak_f32 v55, v55, v51, 0x4b400000
	v_fmaak_f32 v49, v49, v51, 0x4b400000
	v_perm_b32 v46, v46, v52, s3
	v_perm_b32 v47, v47, v53, s33
	v_or_b32_e32 v46, v47, v46
	v_perm_b32 v47, v48, v54, s3
	v_perm_b32 v48, v49, v55, s33
	v_or_b32_e32 v47, v48, v47
	v_lshl_add_u64 v[48:49], v[68:69], 0, s[20:21]
	global_store_dwordx2 v[48:49], v[46:47], off
	v_lshlrev_b32_e32 v46, 16, v42
	v_and_b32_e32 v42, 0xffff0000, v42
	v_lshlrev_b32_e32 v47, 16, v43
	v_and_b32_e32 v43, 0xffff0000, v43
	v_lshlrev_b32_e32 v52, 16, v44
	v_and_b32_e32 v44, 0xffff0000, v44
	v_lshlrev_b32_e32 v53, 16, v45
	v_and_b32_e32 v45, 0xffff0000, v45
	v_fmaak_f32 v46, v46, v51, 0x4b400000
	v_fmaak_f32 v42, v42, v51, 0x4b400000
	v_fmaak_f32 v47, v47, v51, 0x4b400000
	v_fmaak_f32 v43, v43, v51, 0x4b400000
	v_fmaak_f32 v52, v52, v51, 0x4b400000
	v_fmaak_f32 v44, v44, v51, 0x4b400000
	v_fmaak_f32 v53, v53, v51, 0x4b400000
	v_fmaak_f32 v45, v45, v51, 0x4b400000
	v_perm_b32 v42, v42, v46, s3
	v_perm_b32 v43, v43, v47, s33
	v_or_b32_e32 v42, v43, v42
	v_perm_b32 v43, v44, v52, s3
	v_perm_b32 v44, v45, v53, s33
	v_or_b32_e32 v43, v44, v43
	global_store_dwordx2 v[48:49], v[42:43], off offset:512
	v_lshlrev_b32_e32 v42, 16, v38
	v_and_b32_e32 v38, 0xffff0000, v38
	v_lshlrev_b32_e32 v43, 16, v39
	v_and_b32_e32 v39, 0xffff0000, v39
	v_lshlrev_b32_e32 v44, 16, v40
	v_and_b32_e32 v40, 0xffff0000, v40
	v_lshlrev_b32_e32 v45, 16, v41
	v_and_b32_e32 v41, 0xffff0000, v41
	v_fmaak_f32 v42, v42, v51, 0x4b400000
	v_fmaak_f32 v38, v38, v51, 0x4b400000
	v_fmaak_f32 v43, v43, v51, 0x4b400000
	v_fmaak_f32 v39, v39, v51, 0x4b400000
	v_fmaak_f32 v44, v44, v51, 0x4b400000
	v_fmaak_f32 v40, v40, v51, 0x4b400000
	v_fmaak_f32 v45, v45, v51, 0x4b400000
	v_fmaak_f32 v41, v41, v51, 0x4b400000
	v_perm_b32 v38, v38, v42, s3
	v_perm_b32 v39, v39, v43, s33
	v_or_b32_e32 v38, v39, v38
	v_perm_b32 v39, v40, v44, s3
	v_perm_b32 v40, v41, v45, s33
	v_or_b32_e32 v39, v40, v39
	global_store_dwordx2 v[48:49], v[38:39], off offset:1024
	v_lshlrev_b32_e32 v38, 16, v34
	v_and_b32_e32 v34, 0xffff0000, v34
	v_lshlrev_b32_e32 v39, 16, v35
	v_and_b32_e32 v35, 0xffff0000, v35
	v_lshlrev_b32_e32 v40, 16, v36
	v_and_b32_e32 v36, 0xffff0000, v36
	v_lshlrev_b32_e32 v41, 16, v37
	v_and_b32_e32 v37, 0xffff0000, v37
	v_fmaak_f32 v38, v38, v51, 0x4b400000
	v_fmaak_f32 v34, v34, v51, 0x4b400000
	v_fmaak_f32 v39, v39, v51, 0x4b400000
	v_fmaak_f32 v35, v35, v51, 0x4b400000
	v_fmaak_f32 v40, v40, v51, 0x4b400000
	v_fmaak_f32 v36, v36, v51, 0x4b400000
	v_fmaak_f32 v41, v41, v51, 0x4b400000
	v_fmaak_f32 v37, v37, v51, 0x4b400000
	v_perm_b32 v34, v34, v38, s3
	v_perm_b32 v35, v35, v39, s33
	v_or_b32_e32 v34, v35, v34
	v_perm_b32 v35, v36, v40, s3
	v_perm_b32 v36, v37, v41, s33
	v_or_b32_e32 v35, v36, v35
	global_store_dwordx2 v[48:49], v[34:35], off offset:1536
	s_and_saveexec_b64 s[20:21], s[6:7]
	s_cbranch_execz .LBB0_1111
	s_lshl_b64 s[18:19], s[18:19], 2
	s_add_u32 s18, s8, s18
	v_mul_f32_e32 v34, 0x3c010204, v50
	s_addc_u32 s19, s9, s19
	global_store_dword v163, v34, s[18:19]
.LBB0_1111:
	s_or_b64 exec, exec, s[20:21]
	v_and_b32_e32 v36, 0x7fff, v31
	v_bfe_u32 v37, v31, 16, 15
	v_and_b32_e32 v34, 0x7fff, v30
	v_bfe_u32 v35, v30, 16, 15
	v_max_u32_e32 v36, v36, v37
	v_max3_u32 v34, v34, v35, v36
	v_and_b32_e32 v35, 0x7fff, v32
	v_bfe_u32 v36, v32, 16, 15
	v_max_u32_e32 v35, v35, v36
	v_and_b32_e32 v36, 0x7fff, v33
	v_bfe_u32 v37, v33, 16, 15
	v_max_u32_e32 v36, v36, v37
	v_max3_u32 v34, v34, v35, v36
	v_and_b32_e32 v35, 0x7fff, v26
	v_bfe_u32 v36, v26, 16, 15
	v_max_u32_e32 v35, v35, v36
	v_and_b32_e32 v36, 0x7fff, v27
	v_bfe_u32 v37, v27, 16, 15
	v_max_u32_e32 v36, v36, v37
	v_max3_u32 v34, v34, v35, v36
	v_and_b32_e32 v35, 0x7fff, v28
	v_bfe_u32 v36, v28, 16, 15
	v_max_u32_e32 v35, v35, v36
	v_and_b32_e32 v36, 0x7fff, v29
	v_bfe_u32 v37, v29, 16, 15
	v_max_u32_e32 v36, v36, v37
	v_max3_u32 v34, v34, v35, v36
	v_and_b32_e32 v35, 0x7fff, v22
	v_bfe_u32 v36, v22, 16, 15
	v_max_u32_e32 v35, v35, v36
	v_and_b32_e32 v36, 0x7fff, v23
	v_bfe_u32 v37, v23, 16, 15
	v_max_u32_e32 v36, v36, v37
	v_max3_u32 v34, v34, v35, v36
	v_and_b32_e32 v35, 0x7fff, v24
	v_bfe_u32 v36, v24, 16, 15
	v_max_u32_e32 v35, v35, v36
	v_and_b32_e32 v36, 0x7fff, v25
	v_bfe_u32 v37, v25, 16, 15
	v_max_u32_e32 v36, v36, v37
	v_max3_u32 v34, v34, v35, v36
	v_and_b32_e32 v35, 0x7fff, v18
	v_bfe_u32 v36, v18, 16, 15
	v_max_u32_e32 v35, v35, v36
	v_and_b32_e32 v36, 0x7fff, v19
	v_bfe_u32 v37, v19, 16, 15
	v_max_u32_e32 v36, v36, v37
	v_max3_u32 v34, v34, v35, v36
	v_and_b32_e32 v35, 0x7fff, v20
	v_bfe_u32 v36, v20, 16, 15
	v_max_u32_e32 v35, v35, v36
	v_and_b32_e32 v36, 0x7fff, v21
	v_bfe_u32 v37, v21, 16, 15
	v_max_u32_e32 v36, v36, v37
	v_max3_u32 v34, v34, v35, v36
	s_waitcnt lgkmcnt(0)
; __device__ __forceinline__ void quant_rows(const bf16_t* xb, unsigned char* xq, float* qs, const float* ssq, unsigned* cnt, int pm, int quarter, LAS float* rsl, int tid_) {
;     ...
;         for (int q = 0; q < 4; ++q) {
;             unsigned mx = 0u;
; #pragma unroll
;             for (int j = 0; j < 4; ++j)
; #pragma unroll
;                 for (int e = 0; e < 4; ++e) { const unsigned w = v[q][j][e]; mx = max(mx, max(w & 0x7fffu, (w >> 16) & 0x7fffu)); }
; #pragma unroll
;             for (int o = 1; o < 64; o <<= 1) mx = max(mx, (unsigned)__shfl_xor((int)mx, o));
;             const float amax = __uint_as_float(mx << 16);
;             const float inv = mx ? 127.0f / amax : 0.f;
; #pragma unroll
;             for (int j = 0; j < 4; ++j) { float f[8]; unpack8(v[q][j], f); unsigned b[8];
; #pragma unroll
;                 for (int e = 0; e < 8; ++e) b[e] = __float_as_uint(__builtin_fmaf(f[e], inv, QMAGIC));
;                 u32x2 o; o.x = pack4q(b[0], b[1], b[2], b[3]); o.y = pack4q(b[4], b[5], b[6], b[7]);
;                 *(u32x2*)(xq + (size_t)(rbase + q) * DM + (j * 64 + lane) * 8) = o; }
;             if (lane == 0) qs[rbase + q] = amax * (1.0f / 127.0f);
	s_nop 1
	v_max_u32_dpp v34, v34, v34 quad_perm:[1,0,3,2] row_mask:0xf bank_mask:0xf
	s_waitcnt lgkmcnt(0)
	s_nop 1
	v_max_u32_dpp v34, v34, v34 quad_perm:[2,3,0,1] row_mask:0xf bank_mask:0xf
	s_waitcnt lgkmcnt(0)
	s_nop 1
	v_max_u32_dpp v34, v34, v34 row_half_mirror row_mask:0xf bank_mask:0xf
	s_waitcnt lgkmcnt(0)
	s_nop 1
	v_max_u32_dpp v34, v34, v34 row_mirror row_mask:0xf bank_mask:0xf
	s_waitcnt lgkmcnt(0)
	v_mov_b32_e32 v35, v34
	s_nop 1
	v_permlane16_swap_b32_e32 v34, v35
	v_max_u32_e32 v34, v34, v35
	s_waitcnt lgkmcnt(0)
	v_mov_b32_e32 v35, v34
	s_nop 1
	v_permlane32_swap_b32_e32 v34, v35
	v_max_u32_e32 v35, v34, v35
	v_lshlrev_b32_e32 v34, 16, v35
	v_div_scale_f32 v36, s[18:19], v34, v34, s87
	v_rcp_f32_e32 v37, v36
	s_lshl_b64 s[18:19], s[16:17], 11
	v_fma_f32 v38, -v36, v37, 1.0
	v_fmac_f32_e32 v37, v38, v37
	v_div_scale_f32 v38, vcc, s87, v34, s87
	v_mul_f32_e32 v39, v38, v37
	v_fma_f32 v40, -v36, v39, v38
	v_fmac_f32_e32 v39, v40, v37
	v_fma_f32 v36, -v36, v39, v38
	v_div_fmas_f32 v36, v36, v37, v39
	v_div_fixup_f32 v36, v36, v34, s87
	v_cmp_ne_u32_e32 vcc, 0, v35
	v_lshlrev_b32_e32 v37, 16, v31
	v_and_b32_e32 v31, 0xffff0000, v31
	v_cndmask_b32_e32 v35, 0, v36, vcc
	v_lshlrev_b32_e32 v36, 16, v30
	v_and_b32_e32 v30, 0xffff0000, v30
	v_lshlrev_b32_e32 v38, 16, v32
	v_and_b32_e32 v32, 0xffff0000, v32
	v_lshlrev_b32_e32 v39, 16, v33
	v_and_b32_e32 v33, 0xffff0000, v33
	v_fmaak_f32 v36, v36, v35, 0x4b400000
	v_fmaak_f32 v30, v30, v35, 0x4b400000
	v_fmaak_f32 v37, v37, v35, 0x4b400000
	v_fmaak_f32 v31, v31, v35, 0x4b400000
	v_fmaak_f32 v38, v38, v35, 0x4b400000
	v_fmaak_f32 v32, v32, v35, 0x4b400000
	v_fmaak_f32 v39, v39, v35, 0x4b400000
	v_fmaak_f32 v33, v33, v35, 0x4b400000
	v_perm_b32 v30, v30, v36, s3
	v_perm_b32 v31, v31, v37, s33
	v_or_b32_e32 v30, v31, v30
	v_perm_b32 v31, v32, v38, s3
	v_perm_b32 v32, v33, v39, s33
	v_or_b32_e32 v31, v32, v31
	v_lshl_add_u64 v[32:33], v[68:69], 0, s[18:19]
	global_store_dwordx2 v[32:33], v[30:31], off
	v_lshlrev_b32_e32 v30, 16, v26
	v_and_b32_e32 v26, 0xffff0000, v26
	v_lshlrev_b32_e32 v31, 16, v27
	v_and_b32_e32 v27, 0xffff0000, v27
	v_lshlrev_b32_e32 v36, 16, v28
	v_and_b32_e32 v28, 0xffff0000, v28
	v_lshlrev_b32_e32 v37, 16, v29
	v_and_b32_e32 v29, 0xffff0000, v29
	v_fmaak_f32 v30, v30, v35, 0x4b400000
	v_fmaak_f32 v26, v26, v35, 0x4b400000
	v_fmaak_f32 v31, v31, v35, 0x4b400000
	v_fmaak_f32 v27, v27, v35, 0x4b400000
	v_fmaak_f32 v36, v36, v35, 0x4b400000
	v_fmaak_f32 v28, v28, v35, 0x4b400000
	v_fmaak_f32 v37, v37, v35, 0x4b400000
	v_fmaak_f32 v29, v29, v35, 0x4b400000
	v_perm_b32 v26, v26, v30, s3
	v_perm_b32 v27, v27, v31, s33
	v_or_b32_e32 v26, v27, v26
	v_perm_b32 v27, v28, v36, s3
	v_perm_b32 v28, v29, v37, s33
	v_or_b32_e32 v27, v28, v27
	global_store_dwordx2 v[32:33], v[26:27], off offset:512
	v_lshlrev_b32_e32 v26, 16, v22
	v_and_b32_e32 v22, 0xffff0000, v22
	v_lshlrev_b32_e32 v27, 16, v23
	v_and_b32_e32 v23, 0xffff0000, v23
	v_lshlrev_b32_e32 v28, 16, v24
	v_and_b32_e32 v24, 0xffff0000, v24
	v_lshlrev_b32_e32 v29, 16, v25
	v_and_b32_e32 v25, 0xffff0000, v25
	v_fmaak_f32 v26, v26, v35, 0x4b400000
	v_fmaak_f32 v22, v22, v35, 0x4b400000
	v_fmaak_f32 v27, v27, v35, 0x4b400000
	v_fmaak_f32 v23, v23, v35, 0x4b400000
	v_fmaak_f32 v28, v28, v35, 0x4b400000
	v_fmaak_f32 v24, v24, v35, 0x4b400000
	v_fmaak_f32 v29, v29, v35, 0x4b400000
	v_fmaak_f32 v25, v25, v35, 0x4b400000
	v_perm_b32 v22, v22, v26, s3
	v_perm_b32 v23, v23, v27, s33
	v_or_b32_e32 v22, v23, v22
	v_perm_b32 v23, v24, v28, s3
	v_perm_b32 v24, v25, v29, s33
	v_or_b32_e32 v23, v24, v23
	global_store_dwordx2 v[32:33], v[22:23], off offset:1024
	v_lshlrev_b32_e32 v22, 16, v18
	v_and_b32_e32 v18, 0xffff0000, v18
	v_lshlrev_b32_e32 v23, 16, v19
	v_and_b32_e32 v19, 0xffff0000, v19
	v_lshlrev_b32_e32 v24, 16, v20
	v_and_b32_e32 v20, 0xffff0000, v20
	v_lshlrev_b32_e32 v25, 16, v21
	v_and_b32_e32 v21, 0xffff0000, v21
	v_fmaak_f32 v22, v22, v35, 0x4b400000
	v_fmaak_f32 v18, v18, v35, 0x4b400000
	v_fmaak_f32 v23, v23, v35, 0x4b400000
	v_fmaak_f32 v19, v19, v35, 0x4b400000
	v_fmaak_f32 v24, v24, v35, 0x4b400000
	v_fmaak_f32 v20, v20, v35, 0x4b400000
	v_fmaak_f32 v25, v25, v35, 0x4b400000
	v_fmaak_f32 v21, v21, v35, 0x4b400000
	v_perm_b32 v18, v18, v22, s3
	v_perm_b32 v19, v19, v23, s33
	v_or_b32_e32 v18, v19, v18
	v_perm_b32 v19, v20, v24, s3
	v_perm_b32 v20, v21, v25, s33
	v_or_b32_e32 v19, v20, v19
	global_store_dwordx2 v[32:33], v[18:19], off offset:1536
	s_and_saveexec_b64 s[18:19], s[6:7]
	s_cbranch_execz .LBB0_1113
	s_lshl_b64 s[16:17], s[16:17], 2
	s_add_u32 s16, s8, s16
	v_mul_f32_e32 v18, 0x3c010204, v34
	s_addc_u32 s17, s9, s17
	global_store_dword v163, v18, s[16:17]
; __device__ __forceinline__ void quant_rows(const bf16_t* xb, unsigned char* xq, float* qs, const float* ssq, unsigned* cnt, int pm, int quarter, LAS float* rsl, int tid_) {
;     ...
;         for (int q = 0; q < 4; ++q) {
;             unsigned mx = 0u;
; #pragma unroll
;             for (int j = 0; j < 4; ++j)
; #pragma unroll
;                 for (int e = 0; e < 4; ++e) { const unsigned w = v[q][j][e]; mx = max(mx, max(w & 0x7fffu, (w >> 16) & 0x7fffu)); }
; #pragma unroll
;             for (int o = 1; o < 64; o <<= 1) mx = max(mx, (unsigned)__shfl_xor((int)mx, o));
;             const float amax = __uint_as_float(mx << 16);
;             const float inv = mx ? 127.0f / amax : 0.f;
; #pragma unroll
;             for (int j = 0; j < 4; ++j) { float f[8]; unpack8(v[q][j], f); unsigned b[8];
; #pragma unroll
;                 for (int e = 0; e < 8; ++e) b[e] = __float_as_uint(__builtin_fmaf(f[e], inv, QMAGIC));
;                 u32x2 o; o.x = pack4q(b[0], b[1], b[2], b[3]); o.y = pack4q(b[4], b[5], b[6], b[7]);
;                 *(u32x2*)(xq + (size_t)(rbase + q) * DM + (j * 64 + lane) * 8) = o; }
;             if (lane == 0) qs[rbase + q] = amax * (1.0f / 127.0f);
.LBB0_1113:
	s_or_b64 exec, exec, s[18:19]
	v_and_b32_e32 v20, 0x7fff, v15
	v_bfe_u32 v21, v15, 16, 15
	v_and_b32_e32 v18, 0x7fff, v14
	v_bfe_u32 v19, v14, 16, 15
	v_max_u32_e32 v20, v20, v21
	v_max3_u32 v18, v18, v19, v20
	v_and_b32_e32 v19, 0x7fff, v16
	v_bfe_u32 v20, v16, 16, 15
	v_max_u32_e32 v19, v19, v20
	v_and_b32_e32 v20, 0x7fff, v17
	v_bfe_u32 v21, v17, 16, 15
	v_max_u32_e32 v20, v20, v21
	v_max3_u32 v18, v18, v19, v20
	v_and_b32_e32 v19, 0x7fff, v10
	v_bfe_u32 v20, v10, 16, 15
	v_max_u32_e32 v19, v19, v20
	v_and_b32_e32 v20, 0x7fff, v11
	v_bfe_u32 v21, v11, 16, 15
	v_max_u32_e32 v20, v20, v21
	v_max3_u32 v18, v18, v19, v20
	v_and_b32_e32 v19, 0x7fff, v12
	v_bfe_u32 v20, v12, 16, 15
	v_max_u32_e32 v19, v19, v20
	v_and_b32_e32 v20, 0x7fff, v13
	v_bfe_u32 v21, v13, 16, 15
	v_max_u32_e32 v20, v20, v21
	v_max3_u32 v18, v18, v19, v20
	v_and_b32_e32 v19, 0x7fff, v6
	v_bfe_u32 v20, v6, 16, 15
	v_max_u32_e32 v19, v19, v20
	v_and_b32_e32 v20, 0x7fff, v7
	v_bfe_u32 v21, v7, 16, 15
	v_max_u32_e32 v20, v20, v21
	v_max3_u32 v18, v18, v19, v20
	v_and_b32_e32 v19, 0x7fff, v8
	v_bfe_u32 v20, v8, 16, 15
	v_max_u32_e32 v19, v19, v20
	v_and_b32_e32 v20, 0x7fff, v9
	v_bfe_u32 v21, v9, 16, 15
	v_max_u32_e32 v20, v20, v21
	v_max3_u32 v18, v18, v19, v20
	v_and_b32_e32 v19, 0x7fff, v2
	v_bfe_u32 v20, v2, 16, 15
	v_max_u32_e32 v19, v19, v20
	v_and_b32_e32 v20, 0x7fff, v3
	v_bfe_u32 v21, v3, 16, 15
	v_max_u32_e32 v20, v20, v21
	v_max3_u32 v18, v18, v19, v20
	v_and_b32_e32 v19, 0x7fff, v4
	v_bfe_u32 v20, v4, 16, 15
	v_max_u32_e32 v19, v19, v20
	v_and_b32_e32 v20, 0x7fff, v5
	v_bfe_u32 v21, v5, 16, 15
	v_max_u32_e32 v20, v20, v21
	v_max3_u32 v18, v18, v19, v20
	s_waitcnt lgkmcnt(0)
	s_nop 1
	v_max_u32_dpp v18, v18, v18 quad_perm:[1,0,3,2] row_mask:0xf bank_mask:0xf
	s_waitcnt lgkmcnt(0)
	s_nop 1
	v_max_u32_dpp v18, v18, v18 quad_perm:[2,3,0,1] row_mask:0xf bank_mask:0xf
	s_waitcnt lgkmcnt(0)
	s_nop 1
	v_max_u32_dpp v18, v18, v18 row_half_mirror row_mask:0xf bank_mask:0xf
	s_waitcnt lgkmcnt(0)
	s_nop 1
	v_max_u32_dpp v18, v18, v18 row_mirror row_mask:0xf bank_mask:0xf
	s_waitcnt lgkmcnt(0)
	v_mov_b32_e32 v19, v18
	s_nop 1
	v_permlane16_swap_b32_e32 v18, v19
	v_max_u32_e32 v18, v18, v19
	s_waitcnt lgkmcnt(0)
	v_mov_b32_e32 v19, v18
	s_nop 1
	v_permlane32_swap_b32_e32 v18, v19
	v_max_u32_e32 v19, v18, v19
	v_lshlrev_b32_e32 v18, 16, v19
	v_div_scale_f32 v20, s[16:17], v18, v18, s87
	v_rcp_f32_e32 v21, v20
	s_lshl_b64 s[16:17], s[14:15], 11
	v_fma_f32 v22, -v20, v21, 1.0
	v_fmac_f32_e32 v21, v22, v21
	v_div_scale_f32 v22, vcc, s87, v18, s87
	v_mul_f32_e32 v23, v22, v21
	v_fma_f32 v24, -v20, v23, v22
	v_fmac_f32_e32 v23, v24, v21
	v_fma_f32 v20, -v20, v23, v22
	v_div_fmas_f32 v20, v20, v21, v23
	v_div_fixup_f32 v20, v20, v18, s87
	v_cmp_ne_u32_e32 vcc, 0, v19
	v_lshlrev_b32_e32 v21, 16, v15
	v_and_b32_e32 v15, 0xffff0000, v15
	v_cndmask_b32_e32 v19, 0, v20, vcc
	v_lshlrev_b32_e32 v20, 16, v14
	v_and_b32_e32 v14, 0xffff0000, v14
	v_lshlrev_b32_e32 v22, 16, v16
	v_and_b32_e32 v16, 0xffff0000, v16
	v_lshlrev_b32_e32 v23, 16, v17
	v_and_b32_e32 v17, 0xffff0000, v17
	v_fmaak_f32 v20, v20, v19, 0x4b400000
	v_fmaak_f32 v14, v14, v19, 0x4b400000
	v_fmaak_f32 v21, v21, v19, 0x4b400000
	v_fmaak_f32 v15, v15, v19, 0x4b400000
	v_fmaak_f32 v22, v22, v19, 0x4b400000
	v_fmaak_f32 v16, v16, v19, 0x4b400000
	v_fmaak_f32 v23, v23, v19, 0x4b400000
	v_fmaak_f32 v17, v17, v19, 0x4b400000
	v_perm_b32 v14, v14, v20, s3
	v_perm_b32 v15, v15, v21, s33
	v_or_b32_e32 v14, v15, v14
	v_perm_b32 v15, v16, v22, s3
	v_perm_b32 v16, v17, v23, s33
	v_or_b32_e32 v15, v16, v15
	v_lshl_add_u64 v[16:17], v[68:69], 0, s[16:17]
	global_store_dwordx2 v[16:17], v[14:15], off
	v_lshlrev_b32_e32 v14, 16, v10
	v_and_b32_e32 v10, 0xffff0000, v10
	v_lshlrev_b32_e32 v15, 16, v11
	v_and_b32_e32 v11, 0xffff0000, v11
	v_lshlrev_b32_e32 v20, 16, v12
	v_and_b32_e32 v12, 0xffff0000, v12
	v_lshlrev_b32_e32 v21, 16, v13
	v_and_b32_e32 v13, 0xffff0000, v13
	v_fmaak_f32 v14, v14, v19, 0x4b400000
	v_fmaak_f32 v10, v10, v19, 0x4b400000
	v_fmaak_f32 v15, v15, v19, 0x4b400000
	v_fmaak_f32 v11, v11, v19, 0x4b400000
	v_fmaak_f32 v20, v20, v19, 0x4b400000
	v_fmaak_f32 v12, v12, v19, 0x4b400000
	v_fmaak_f32 v21, v21, v19, 0x4b400000
	v_fmaak_f32 v13, v13, v19, 0x4b400000
	v_perm_b32 v10, v10, v14, s3
	v_perm_b32 v11, v11, v15, s33
	v_or_b32_e32 v10, v11, v10
	v_perm_b32 v11, v12, v20, s3
	v_perm_b32 v12, v13, v21, s33
	v_or_b32_e32 v11, v12, v11
	global_store_dwordx2 v[16:17], v[10:11], off offset:512
	v_lshlrev_b32_e32 v10, 16, v6
	v_and_b32_e32 v6, 0xffff0000, v6
	v_lshlrev_b32_e32 v11, 16, v7
	v_and_b32_e32 v7, 0xffff0000, v7
	v_lshlrev_b32_e32 v12, 16, v8
	v_and_b32_e32 v8, 0xffff0000, v8
	v_lshlrev_b32_e32 v13, 16, v9
	v_and_b32_e32 v9, 0xffff0000, v9
	v_fmaak_f32 v10, v10, v19, 0x4b400000
	v_fmaak_f32 v6, v6, v19, 0x4b400000
	v_fmaak_f32 v11, v11, v19, 0x4b400000
	v_fmaak_f32 v7, v7, v19, 0x4b400000
	v_fmaak_f32 v12, v12, v19, 0x4b400000
	v_fmaak_f32 v8, v8, v19, 0x4b400000
	v_fmaak_f32 v13, v13, v19, 0x4b400000
	v_fmaak_f32 v9, v9, v19, 0x4b400000
	v_perm_b32 v6, v6, v10, s3
	v_perm_b32 v7, v7, v11, s33
	v_or_b32_e32 v6, v7, v6
	v_perm_b32 v7, v8, v12, s3
	v_perm_b32 v8, v9, v13, s33
	v_or_b32_e32 v7, v8, v7
	global_store_dwordx2 v[16:17], v[6:7], off offset:1024
	v_lshlrev_b32_e32 v6, 16, v2
	v_and_b32_e32 v2, 0xffff0000, v2
	v_lshlrev_b32_e32 v7, 16, v3
	v_and_b32_e32 v3, 0xffff0000, v3
	v_lshlrev_b32_e32 v8, 16, v4
	v_and_b32_e32 v4, 0xffff0000, v4
	v_lshlrev_b32_e32 v9, 16, v5
	v_and_b32_e32 v5, 0xffff0000, v5
	v_fmaak_f32 v6, v6, v19, 0x4b400000
	v_fmaak_f32 v2, v2, v19, 0x4b400000
	v_fmaak_f32 v7, v7, v19, 0x4b400000
	v_fmaak_f32 v3, v3, v19, 0x4b400000
	v_fmaak_f32 v8, v8, v19, 0x4b400000
	v_fmaak_f32 v4, v4, v19, 0x4b400000
	v_fmaak_f32 v9, v9, v19, 0x4b400000
	v_fmaak_f32 v5, v5, v19, 0x4b400000
	v_perm_b32 v2, v2, v6, s3
	v_perm_b32 v3, v3, v7, s33
	v_or_b32_e32 v2, v3, v2
	v_perm_b32 v3, v4, v8, s3
	v_perm_b32 v4, v5, v9, s33
	v_or_b32_e32 v3, v4, v3
	global_store_dwordx2 v[16:17], v[2:3], off offset:1536
	s_and_saveexec_b64 s[16:17], s[6:7]
	s_cbranch_execz .LBB0_1106
	s_lshl_b64 s[14:15], s[14:15], 2
	s_add_u32 s14, s8, s14
	v_mul_f32_e32 v2, 0x3c010204, v18
	s_addc_u32 s15, s9, s15
	global_store_dword v163, v2, s[14:15]
	s_branch .LBB0_1106
